# peel first K-tile of G1/S/G4/G5 K-loops: first-touch MFMAs take C=0, accumulator zeroing removed from those unit pre-headers (others keep v_pk_mov zeroing)
# speedup vs baseline: 1.0067x; 1.0031x over previous
; #define G8_STA(bufoff, ptr, sg, h) G8_STAGE1(bufoff, (ptr) + (h) * ((sg) ? hA1 : hA0), ((sg) ? voffA1 : voffA0), ((sg) ? r64A1 : r64A0))
; #define G8_LDA(dst, b, h) do { _Pragma("unroll") for (int m = 0; m < 4; ++m) _Pragma("unroll") for (int k = 0; k < 2; ++k) dst[m][k] = *(const LAS bf16x8*)(lds + G8_SA(b, h) + aoff + m * 2048 + k * 1024); } while (0)
; #define G8_LDB(dst, b, h) do { _Pragma("unroll") for (int n = 0; n < 2; ++n) _Pragma("unroll") for (int k = 0; k < 2; ++k) dst[n][k] = *(const LAS bf16x8*)(lds + G8_SB(b, h) + boff + n * 2048 + k * 1024); } while (0)
; #define G8_MMA(ai, bj, At, Bt) do { __builtin_amdgcn_s_setprio(1); _Pragma("unroll") for (int m = 0; m < 4; ++m) _Pragma("unroll") for (int n = 0; n < 2; ++n) _Pragma("unroll") for (int k = 0; k < 2; ++k) \
;         acc[ai][bj][m][n] = __builtin_amdgcn_mfma_f32_16x16x32_bf16(Bt[n][k], At[m][k], acc[ai][bj][m][n], 0, 0, 0); __builtin_amdgcn_s_setprio(0); } while (0)
; #define G8_BAR __builtin_amdgcn_s_barrier()
; template <class P>
; __device__ __forceinline__ void gemm_phase(LAS unsigned char* lds, const P& p, const int G, const int c) {
;     ...
;         const bool has_next = p.unit((ui + 1) * G + c, nxt);
;         const int nt = p.nt(cur);
;         const char* nA0 = has_next ? p.a_base(nxt, 0) - p.a_bias(0) : cA0; const char* nA1 = has_next ? p.a_base(nxt, S1) - p.a_bias(S1) : cA1;
;         const char* nB0 = has_next ? p.b_base(nxt, 0) - p.b_bias(0) : cB0; const char* nB1 = has_next ? p.b_base(nxt, S1) - p.b_bias(S1) : cB1;
;         for (int t = 0; t < nt; t += 2) {
;             const bool last = (t == nt - 2);
;             const bool sg1 = (NS > 1) && (t + 1 >= nt0);
;             const bool sg2 = (NS > 1) && !last && (t + 2 >= nt0);
;             const char* a1 = sg1 ? cA1 + (long)(t + 1 - nt0) * ksA1 : cA0 + (long)(t + 1) * ksA0;
;             const char* a2 = last ? nA0 : (sg2 ? cA1 + (long)(t + 2 - nt0) * ksA1 : cA0 + (long)(t + 2) * ksA0);
;             const char* b2 = last ? nB0 : (sg2 ? cB1 + (long)(t + 2 - nt0) * ksB1 : cB0 + (long)(t + 2) * ksB0);
;             const char* a3 = a2 + (sg2 ? ksA1 : ksA0); const char* b3 = b2 + (sg2 ? ksB1 : ksB0);
;             G8_LDB(B0, 0, 0); G8_LDB(B1, 0, 1); G8_SCHED; G8_LDA(At, 0, 0); G8_STA(G8_SA(1, 1), a1, sg1, 1);
;             G8_WAIT_V(8); G8_WAIT_L(0); G8_BAR; G8_MMA(0, 0, At, B0); G8_MMA(0, 1, At, B1); G8_BAR; G8_SCHED;
.LBB0_154:
	s_cmp_lt_i32 s88, 16
	s_cselect_b64 s[18:19], -1, 0
	s_cmpk_gt_i32 s68, 0x7f
	s_cselect_b64 s[30:31], -1, 0
	s_ashr_i32 s69, s68, 31
	s_or_b64 s[18:19], s[18:19], s[30:31]
	s_lshl_b64 s[30:31], s[68:69], 15
	v_readlane_b32 s52, v253, 7
	s_and_b64 s[18:19], s[18:19], exec
	v_readlane_b32 s66, v253, 21
	v_readlane_b32 s67, v253, 22
	s_cselect_b32 s19, s3, s66
	s_cselect_b32 s18, s24, s67
	s_add_u32 s72, s19, s30
	s_addc_u32 s73, s18, s31
	s_and_b64 s[18:19], s[70:71], exec
	s_cselect_b32 s18, s73, s83
	s_cselect_b32 s19, s72, s82
	s_ashr_i32 s89, s88, 31
	s_lshl_b64 s[30:31], s[88:89], 15
	s_add_u32 s76, s25, s30
	s_addc_u32 s77, s26, s31
	s_and_b64 s[30:31], s[70:71], exec
	s_cselect_b32 s30, s77, s29
	s_cselect_b32 s31, s76, s28
	s_add_u32 s28, s28, 0x200000
	s_addc_u32 s29, s29, 0
	v_lshl_add_u64 v[54:55], s[82:83], 0, v[148:149]
	s_mov_b32 s52, -2
	s_mov_b64 s[84:85], 0
	v_readlane_b32 s53, v253, 8
	v_readlane_b32 s54, v253, 9
	v_readlane_b32 s55, v253, 10
	v_readlane_b32 s56, v253, 11
	v_readlane_b32 s57, v253, 12
	v_readlane_b32 s58, v253, 13
	v_readlane_b32 s59, v253, 14
	v_readlane_b32 s60, v253, 15
	v_readlane_b32 s61, v253, 16
	v_readlane_b32 s62, v253, 17
	v_readlane_b32 s63, v253, 18
	v_readlane_b32 s64, v253, 19
	v_readlane_b32 s65, v253, 20
	ds_read_b128 v[56:59], v173
	ds_read_b128 v[60:63], v173 offset:1024
	ds_read_b128 v[176:179], v173 offset:2048
	ds_read_b128 v[180:183], v173 offset:3072
	ds_read_b128 v[184:187], v174
	ds_read_b128 v[188:191], v174 offset:1024
	ds_read_b128 v[192:195], v174 offset:2048
	ds_read_b128 v[196:199], v174 offset:3072
	s_add_u32 s53, s82, s84
	s_addc_u32 s56, s83, s85
	s_add_u32 s53, s53, 0x820000
	s_addc_u32 s56, s56, 0
	s_cmp_eq_u32 s84, 0x38e0000
	s_cselect_b32 s57, s18, s56
	s_cselect_b32 s56, s19, s53
	s_cselect_b32 s65, s30, s29
	s_cselect_b32 s64, s31, s28
	v_lshl_add_u64 v[64:65], v[54:55], 0, s[84:85]
	s_mov_b64 s[66:67], 0x414000
	v_lshl_add_u64 v[234:235], v[64:65], 0, s[66:67]
	s_add_i32 m0, s27, 0xc000
	s_mov_b64 s[66:67], 0x416000
	ds_read_b128 v[200:203], v175
	ds_read_b128 v[204:207], v175 offset:1024
	ds_read_b128 v[210:213], v175 offset:2048
	ds_read_b128 v[214:217], v175 offset:3072
	ds_read_b128 v[218:221], v175 offset:4096
	ds_read_b128 v[222:225], v175 offset:5120
	ds_read_b128 v[226:229], v175 offset:6144
	ds_read_b128 v[230:233], v175 offset:7168
	global_load_lds_dwordx4 v[234:235], off
	v_lshl_add_u64 v[64:65], v[64:65], 0, s[66:67]
	s_add_i32 m0, s27, 0xe000
	s_nop 0
	global_load_lds_dwordx4 v[64:65], off
	s_waitcnt vmcnt(8)
	s_waitcnt lgkmcnt(0)
	s_barrier
	s_waitcnt lgkmcnt(0)
	v_mfma_f32_16x16x32_bf16 v[98:101], v[56:59], v[200:203], 0
	v_mfma_f32_16x16x32_bf16 v[138:141], v[176:179], v[200:203], 0
	v_mfma_f32_16x16x32_bf16 v[70:73], v[56:59], v[210:213], 0
	v_mfma_f32_16x16x32_bf16 v[114:117], v[176:179], v[210:213], 0
	v_mfma_f32_16x16x32_bf16 v[46:49], v[56:59], v[218:221], 0
	v_mfma_f32_16x16x32_bf16 v[110:113], v[176:179], v[218:221], 0
	v_mfma_f32_16x16x32_bf16 v[38:41], v[56:59], v[226:229], 0
	v_mfma_f32_16x16x32_bf16 v[130:133], v[176:179], v[226:229], 0
	v_mfma_f32_16x16x32_bf16 v[98:101], v[60:63], v[204:207], v[98:101]
	v_mfma_f32_16x16x32_bf16 v[138:141], v[180:183], v[204:207], v[138:141]
	v_mfma_f32_16x16x32_bf16 v[70:73], v[60:63], v[214:217], v[70:73]
	v_mfma_f32_16x16x32_bf16 v[114:117], v[180:183], v[214:217], v[114:117]
	v_mfma_f32_16x16x32_bf16 v[46:49], v[60:63], v[222:225], v[46:49]
	v_mfma_f32_16x16x32_bf16 v[110:113], v[180:183], v[222:225], v[110:113]
	v_mfma_f32_16x16x32_bf16 v[38:41], v[60:63], v[230:233], v[38:41]
	v_mfma_f32_16x16x32_bf16 v[130:133], v[180:183], v[230:233], v[130:133]
	v_mfma_f32_16x16x32_bf16 v[134:137], v[184:187], v[200:203], 0
	v_mfma_f32_16x16x32_bf16 v[74:77], v[192:195], v[200:203], 0
	v_mfma_f32_16x16x32_bf16 v[106:109], v[184:187], v[210:213], 0
	v_mfma_f32_16x16x32_bf16 v[50:53], v[192:195], v[210:213], 0
	v_mfma_f32_16x16x32_bf16 v[102:105], v[184:187], v[218:221], 0
	v_mfma_f32_16x16x32_bf16 v[42:45], v[192:195], v[218:221], 0
	v_mfma_f32_16x16x32_bf16 v[126:129], v[184:187], v[226:229], 0
	v_mfma_f32_16x16x32_bf16 v[34:37], v[192:195], v[226:229], 0
	v_mfma_f32_16x16x32_bf16 v[134:137], v[188:191], v[204:207], v[134:137]
	v_mfma_f32_16x16x32_bf16 v[74:77], v[196:199], v[204:207], v[74:77]
	v_mfma_f32_16x16x32_bf16 v[106:109], v[188:191], v[214:217], v[106:109]
	v_mfma_f32_16x16x32_bf16 v[50:53], v[196:199], v[214:217], v[50:53]
	v_mfma_f32_16x16x32_bf16 v[102:105], v[188:191], v[222:225], v[102:105]
	v_mfma_f32_16x16x32_bf16 v[42:45], v[196:199], v[222:225], v[42:45]
	v_mfma_f32_16x16x32_bf16 v[126:129], v[188:191], v[230:233], v[126:129]
	v_mfma_f32_16x16x32_bf16 v[34:37], v[196:199], v[230:233], v[34:37]
	s_barrier
; #define G8_STA(bufoff, ptr, sg, h) G8_STAGE1(bufoff, (ptr) + (h) * ((sg) ? hA1 : hA0), ((sg) ? voffA1 : voffA0), ((sg) ? r64A1 : r64A0))
; #define G8_STB(bufoff, ptr, sg, h) G8_STAGE1(bufoff, (ptr) + (h) * ((sg) ? hB1 : hB0), ((sg) ? voffB1 : voffB0), ((sg) ? r64B1 : r64B0))
; #define G8_LDA(dst, b, h) do { _Pragma("unroll") for (int m = 0; m < 4; ++m) _Pragma("unroll") for (int k = 0; k < 2; ++k) dst[m][k] = *(const LAS bf16x8*)(lds + G8_SA(b, h) + aoff + m * 2048 + k * 1024); } while (0)
; #define G8_MMA(ai, bj, At, Bt) do { __builtin_amdgcn_s_setprio(1); _Pragma("unroll") for (int m = 0; m < 4; ++m) _Pragma("unroll") for (int n = 0; n < 2; ++n) _Pragma("unroll") for (int k = 0; k < 2; ++k) \
;         acc[ai][bj][m][n] = __builtin_amdgcn_mfma_f32_16x16x32_bf16(Bt[n][k], At[m][k], acc[ai][bj][m][n], 0, 0, 0); __builtin_amdgcn_s_setprio(0); } while (0)
; #define G8_WAIT_V(n) asm volatile("s_waitcnt vmcnt(" #n ")" ::: "memory")
; #define G8_WAIT_L(n) asm volatile("s_waitcnt lgkmcnt(" #n ")" ::: "memory")
; #define G8_BAR __builtin_amdgcn_s_barrier()
; #define G8_SCHED __builtin_amdgcn_sched_barrier(0)
; template <class P>
; __device__ __forceinline__ void gemm_phase(LAS unsigned char* lds, const P& p, const int G, const int c) {
;     ...
;             G8_LDA(At, 0, 1); G8_STB(G8_SB(0, 0), b2, sg2, 0); G8_STB(G8_SB(0, 1), b2, sg2, 1); G8_STA(G8_SA(0, 0), a2, sg2, 0);
;             G8_WAIT_V(8); G8_WAIT_L(0); G8_BAR; G8_MMA(1, 0, At, B0); G8_MMA(1, 1, At, B1); G8_BAR; G8_SCHED;
	s_add_i32 s53, s50, s2
	v_lshl_add_u64 v[234:235], s[64:65], 0, v[142:143]
	s_mov_b32 m0, s53
	ds_read_b128 v[200:203], v175 offset:16384
	ds_read_b128 v[204:207], v175 offset:17408
	ds_read_b128 v[210:213], v175 offset:18432
	ds_read_b128 v[214:217], v175 offset:19456
	ds_read_b128 v[218:221], v175 offset:20480
	ds_read_b128 v[222:225], v175 offset:21504
	ds_read_b128 v[226:229], v175 offset:22528
	ds_read_b128 v[230:233], v175 offset:23552
	global_load_lds_dwordx4 v[234:235], off
	v_lshl_add_u64 v[64:65], v[234:235], 0, s[4:5]
	s_add_i32 m0, s53, 0x2000
	s_add_i32 s53, s51, s2
	global_load_lds_dwordx4 v[64:65], off
	v_lshl_add_u64 v[64:65], v[234:235], 0, s[6:7]
	s_mov_b32 m0, s53
	v_lshl_add_u64 v[236:237], s[56:57], 0, v[144:145]
	global_load_lds_dwordx4 v[64:65], off
	v_lshl_add_u64 v[64:65], v[234:235], 0, s[8:9]
	s_add_i32 m0, s53, 0x2000
	s_nop 0
	global_load_lds_dwordx4 v[64:65], off
	s_mov_b32 m0, s27
	v_lshl_add_u64 v[64:65], v[236:237], 0, s[4:5]
	global_load_lds_dwordx4 v[236:237], off
	s_mov_b32 m0, s33
	s_nop 0
	global_load_lds_dwordx4 v[64:65], off
	s_waitcnt vmcnt(8)
	s_waitcnt lgkmcnt(0)
	s_barrier
	s_waitcnt lgkmcnt(0)
	v_mfma_f32_16x16x32_bf16 v[30:33], v[56:59], v[200:203], 0
	v_mfma_f32_16x16x32_bf16 v[122:125], v[176:179], v[200:203], 0
	v_mfma_f32_16x16x32_bf16 v[22:25], v[56:59], v[210:213], 0
	v_mfma_f32_16x16x32_bf16 v[94:97], v[176:179], v[210:213], 0
	v_mfma_f32_16x16x32_bf16 v[14:17], v[56:59], v[218:221], 0
	v_mfma_f32_16x16x32_bf16 v[90:93], v[176:179], v[218:221], 0
	v_mfma_f32_16x16x32_bf16 v[6:9], v[56:59], v[226:229], 0
	v_mfma_f32_16x16x32_bf16 v[30:33], v[60:63], v[204:207], v[30:33]
	v_mfma_f32_16x16x32_bf16 v[122:125], v[180:183], v[204:207], v[122:125]
	v_mfma_f32_16x16x32_bf16 v[22:25], v[60:63], v[214:217], v[22:25]
	v_mfma_f32_16x16x32_bf16 v[94:97], v[180:183], v[214:217], v[94:97]
	v_mfma_f32_16x16x32_bf16 v[14:17], v[60:63], v[222:225], v[14:17]
	v_mfma_f32_16x16x32_bf16 v[90:93], v[180:183], v[222:225], v[90:93]
	v_mfma_f32_16x16x32_bf16 v[6:9], v[60:63], v[230:233], v[6:9]
	v_mfma_f32_16x16x32_bf16 v[56:59], v[176:179], v[226:229], 0
	v_mfma_f32_16x16x32_bf16 v[56:59], v[180:183], v[230:233], v[56:59]
	v_mfma_f32_16x16x32_bf16 v[78:81], v[184:187], v[210:213], 0
	v_mfma_f32_16x16x32_bf16 v[26:29], v[192:195], v[200:203], 0
	v_mfma_f32_16x16x32_bf16 v[86:89], v[188:191], v[214:217], v[78:81]
	v_mfma_f32_16x16x32_bf16 v[18:21], v[192:195], v[210:213], 0
	v_mfma_f32_16x16x32_bf16 v[78:81], v[184:187], v[218:221], 0
	v_mfma_f32_16x16x32_bf16 v[10:13], v[192:195], v[218:221], 0
	v_mfma_f32_16x16x32_bf16 v[64:67], v[184:187], v[226:229], 0
	v_mfma_f32_16x16x32_bf16 v[2:5], v[192:195], v[226:229], 0
	v_mfma_f32_16x16x32_bf16 v[60:63], v[184:187], v[200:203], 0
	v_mfma_f32_16x16x32_bf16 v[26:29], v[196:199], v[204:207], v[26:29]
	v_mfma_f32_16x16x32_bf16 v[18:21], v[196:199], v[214:217], v[18:21]
	v_mfma_f32_16x16x32_bf16 v[82:85], v[188:191], v[222:225], v[78:81]
	v_mfma_f32_16x16x32_bf16 v[10:13], v[196:199], v[222:225], v[10:13]
	v_mfma_f32_16x16x32_bf16 v[64:67], v[188:191], v[230:233], v[64:67]
	v_mfma_f32_16x16x32_bf16 v[2:5], v[196:199], v[230:233], v[2:5]
	v_mfma_f32_16x16x32_bf16 v[60:63], v[188:191], v[204:207], v[60:63]
	s_branch .Lmid_155

; #define G8_STA(bufoff, ptr, sg, h) G8_STAGE1(bufoff, (ptr) + (h) * ((sg) ? hA1 : hA0), ((sg) ? voffA1 : voffA0), ((sg) ? r64A1 : r64A0))
; #define G8_STB(bufoff, ptr, sg, h) G8_STAGE1(bufoff, (ptr) + (h) * ((sg) ? hB1 : hB0), ((sg) ? voffB1 : voffB0), ((sg) ? r64B1 : r64B0))
; #define G8_LDA(dst, b, h) do { _Pragma("unroll") for (int m = 0; m < 4; ++m) _Pragma("unroll") for (int k = 0; k < 2; ++k) dst[m][k] = *(const LAS bf16x8*)(lds + G8_SA(b, h) + aoff + m * 2048 + k * 1024); } while (0)
; #define G8_LDB(dst, b, h) do { _Pragma("unroll") for (int n = 0; n < 2; ++n) _Pragma("unroll") for (int k = 0; k < 2; ++k) dst[n][k] = *(const LAS bf16x8*)(lds + G8_SB(b, h) + boff + n * 2048 + k * 1024); } while (0)
; #define G8_MMA(ai, bj, At, Bt) do { __builtin_amdgcn_s_setprio(1); _Pragma("unroll") for (int m = 0; m < 4; ++m) _Pragma("unroll") for (int n = 0; n < 2; ++n) _Pragma("unroll") for (int k = 0; k < 2; ++k) \
;         acc[ai][bj][m][n] = __builtin_amdgcn_mfma_f32_16x16x32_bf16(Bt[n][k], At[m][k], acc[ai][bj][m][n], 0, 0, 0); __builtin_amdgcn_s_setprio(0); } while (0)
; #define G8_WAIT_V(n) asm volatile("s_waitcnt vmcnt(" #n ")" ::: "memory")
; #define G8_WAIT_L(n) asm volatile("s_waitcnt lgkmcnt(" #n ")" ::: "memory")
; #define G8_BAR __builtin_amdgcn_s_barrier()
; #define G8_SCHED __builtin_amdgcn_sched_barrier(0)
; template <class P>
; __device__ __forceinline__ void gemm_phase(LAS unsigned char* lds, const P& p, const int G, const int c) {
;     ...
;             G8_LDB(B0, 1, 0); G8_LDB(B1, 1, 1); G8_SCHED; G8_LDA(At, 1, 0); G8_STA(G8_SA(0, 1), a2, sg2, 1);
;             G8_WAIT_V(8); G8_WAIT_L(0); G8_BAR; G8_MMA(0, 0, At, B0); G8_MMA(0, 1, At, B1); G8_BAR; G8_SCHED;
;             G8_LDA(At, 1, 1); G8_STB(G8_SB(1, 0), b3, sg2, 0); G8_STB(G8_SB(1, 1), b3, sg2, 1); G8_STA(G8_SA(1, 0), a3, sg2, 0);
;             G8_WAIT_V(8); G8_WAIT_L(0); G8_BAR; G8_MMA(1, 0, At, B0); G8_MMA(1, 1, At, B1); G8_BAR; G8_SCHED;
;         }
.Lmid_155:
	s_barrier
	s_add_i32 s53, 0, 0x18000
	v_add_u32_e32 v68, s53, v152
	s_add_i32 s56, 0, 0x1c000
	ds_read_b128 v[78:81], v68
	ds_read_b128 v[118:121], v68 offset:1024
	ds_read_b128 v[176:179], v68 offset:2048
	ds_read_b128 v[180:183], v68 offset:3072
	v_add_u32_e32 v68, s56, v152
	ds_read_b128 v[184:187], v68
	ds_read_b128 v[188:191], v68 offset:1024
	ds_read_b128 v[192:195], v68 offset:2048
	ds_read_b128 v[196:199], v68 offset:3072
	s_mov_b32 m0, s34
	v_lshl_add_u64 v[68:69], v[236:237], 0, s[6:7]
	ds_read_b128 v[200:203], v175 offset:32768
	ds_read_b128 v[204:207], v175 offset:33792
	ds_read_b128 v[210:213], v175 offset:34816
	ds_read_b128 v[214:217], v175 offset:35840
	ds_read_b128 v[218:221], v175 offset:36864
	ds_read_b128 v[222:225], v175 offset:37888
	ds_read_b128 v[226:229], v175 offset:38912
	ds_read_b128 v[230:233], v175 offset:39936
	global_load_lds_dwordx4 v[68:69], off
	v_lshl_add_u64 v[68:69], v[236:237], 0, s[8:9]
	s_mov_b32 m0, s35
	s_nop 0
	global_load_lds_dwordx4 v[68:69], off
	s_waitcnt vmcnt(8)
	s_waitcnt lgkmcnt(0)
	s_barrier
	s_waitcnt lgkmcnt(0)
	v_mfma_f32_16x16x32_bf16 v[98:101], v[78:81], v[200:203], v[98:101]
	v_mfma_f32_16x16x32_bf16 v[138:141], v[176:179], v[200:203], v[138:141]
	v_mfma_f32_16x16x32_bf16 v[68:71], v[78:81], v[210:213], v[70:73]
	v_mfma_f32_16x16x32_bf16 v[114:117], v[176:179], v[210:213], v[114:117]
	v_mfma_f32_16x16x32_bf16 v[46:49], v[78:81], v[218:221], v[46:49]
	v_mfma_f32_16x16x32_bf16 v[110:113], v[176:179], v[218:221], v[110:113]
	v_mfma_f32_16x16x32_bf16 v[38:41], v[78:81], v[226:229], v[38:41]
	v_mfma_f32_16x16x32_bf16 v[130:133], v[176:179], v[226:229], v[130:133]
	v_mfma_f32_16x16x32_bf16 v[98:101], v[118:121], v[204:207], v[98:101]
	v_mfma_f32_16x16x32_bf16 v[138:141], v[180:183], v[204:207], v[138:141]
	v_mfma_f32_16x16x32_bf16 v[70:73], v[118:121], v[214:217], v[68:71]
	v_mfma_f32_16x16x32_bf16 v[114:117], v[180:183], v[214:217], v[114:117]
	v_mfma_f32_16x16x32_bf16 v[46:49], v[118:121], v[222:225], v[46:49]
	v_mfma_f32_16x16x32_bf16 v[110:113], v[180:183], v[222:225], v[110:113]
	v_mfma_f32_16x16x32_bf16 v[38:41], v[118:121], v[230:233], v[38:41]
	v_mfma_f32_16x16x32_bf16 v[130:133], v[180:183], v[230:233], v[130:133]
	v_mfma_f32_16x16x32_bf16 v[134:137], v[184:187], v[200:203], v[134:137]
	v_mfma_f32_16x16x32_bf16 v[74:77], v[192:195], v[200:203], v[74:77]
	v_mfma_f32_16x16x32_bf16 v[106:109], v[184:187], v[210:213], v[106:109]
	v_mfma_f32_16x16x32_bf16 v[50:53], v[192:195], v[210:213], v[50:53]
	v_mfma_f32_16x16x32_bf16 v[102:105], v[184:187], v[218:221], v[102:105]
	v_mfma_f32_16x16x32_bf16 v[42:45], v[192:195], v[218:221], v[42:45]
	v_mfma_f32_16x16x32_bf16 v[126:129], v[184:187], v[226:229], v[126:129]
	v_mfma_f32_16x16x32_bf16 v[34:37], v[192:195], v[226:229], v[34:37]
	v_mfma_f32_16x16x32_bf16 v[134:137], v[188:191], v[204:207], v[134:137]
	v_mfma_f32_16x16x32_bf16 v[74:77], v[196:199], v[204:207], v[74:77]
	v_mfma_f32_16x16x32_bf16 v[106:109], v[188:191], v[214:217], v[106:109]
	v_mfma_f32_16x16x32_bf16 v[50:53], v[196:199], v[214:217], v[50:53]
	v_mfma_f32_16x16x32_bf16 v[102:105], v[188:191], v[222:225], v[102:105]
	v_mfma_f32_16x16x32_bf16 v[42:45], v[196:199], v[222:225], v[42:45]
	v_mfma_f32_16x16x32_bf16 v[126:129], v[188:191], v[230:233], v[126:129]
	v_mfma_f32_16x16x32_bf16 v[34:37], v[196:199], v[230:233], v[34:37]
	s_barrier
	s_add_i32 s53, s53, s2
	v_lshl_add_u64 v[68:69], v[234:235], 0, s[12:13]
	s_mov_b32 m0, s53
	ds_read_b128 v[200:203], v175 offset:49152
	ds_read_b128 v[204:207], v175 offset:50176
	ds_read_b128 v[210:213], v175 offset:51200
	ds_read_b128 v[214:217], v175 offset:52224
	ds_read_b128 v[218:221], v175 offset:53248
	ds_read_b128 v[222:225], v175 offset:54272
	ds_read_b128 v[226:229], v175 offset:55296
	ds_read_b128 v[230:233], v175 offset:56320
	global_load_lds_dwordx4 v[68:69], off
	v_lshl_add_u64 v[68:69], v[234:235], 0, s[14:15]
	s_add_i32 m0, s53, 0x2000
	s_add_i32 s53, s56, s2
	global_load_lds_dwordx4 v[68:69], off
	v_lshl_add_u64 v[68:69], v[234:235], 0, s[22:23]
	s_mov_b32 m0, s53
	s_nop 0
	global_load_lds_dwordx4 v[68:69], off
	v_lshl_add_u64 v[68:69], v[234:235], 0, s[36:37]
	s_add_i32 m0, s53, 0x2000
	s_nop 0
	global_load_lds_dwordx4 v[68:69], off
	v_lshl_add_u64 v[68:69], v[236:237], 0, s[16:17]
	s_mov_b32 m0, s47
	s_nop 0
	global_load_lds_dwordx4 v[68:69], off
	v_lshl_add_u64 v[68:69], v[236:237], 0, s[20:21]
	s_mov_b32 m0, s48
	s_nop 0
	global_load_lds_dwordx4 v[68:69], off
	s_waitcnt vmcnt(8)
	s_waitcnt lgkmcnt(0)
	s_barrier
	s_waitcnt lgkmcnt(0)
	v_mfma_f32_16x16x32_bf16 v[30:33], v[78:81], v[200:203], v[30:33]
	v_mfma_f32_16x16x32_bf16 v[122:125], v[176:179], v[200:203], v[122:125]
	v_mfma_f32_16x16x32_bf16 v[22:25], v[78:81], v[210:213], v[22:25]
	v_mfma_f32_16x16x32_bf16 v[94:97], v[176:179], v[210:213], v[94:97]
	v_mfma_f32_16x16x32_bf16 v[14:17], v[78:81], v[218:221], v[14:17]
	v_mfma_f32_16x16x32_bf16 v[90:93], v[176:179], v[218:221], v[90:93]
	v_mfma_f32_16x16x32_bf16 v[6:9], v[78:81], v[226:229], v[6:9]
	v_mfma_f32_16x16x32_bf16 v[56:59], v[176:179], v[226:229], v[56:59]
	v_mfma_f32_16x16x32_bf16 v[30:33], v[118:121], v[204:207], v[30:33]
	v_mfma_f32_16x16x32_bf16 v[122:125], v[180:183], v[204:207], v[122:125]
	v_mfma_f32_16x16x32_bf16 v[22:25], v[118:121], v[214:217], v[22:25]
	v_mfma_f32_16x16x32_bf16 v[94:97], v[180:183], v[214:217], v[94:97]
	v_mfma_f32_16x16x32_bf16 v[14:17], v[118:121], v[222:225], v[14:17]
	v_mfma_f32_16x16x32_bf16 v[90:93], v[180:183], v[222:225], v[90:93]
	v_mfma_f32_16x16x32_bf16 v[6:9], v[118:121], v[230:233], v[6:9]
	v_mfma_f32_16x16x32_bf16 v[78:81], v[180:183], v[230:233], v[56:59]
	v_mfma_f32_16x16x32_bf16 v[56:59], v[184:187], v[200:203], v[60:63]
	v_mfma_f32_16x16x32_bf16 v[118:121], v[188:191], v[204:207], v[56:59]
	v_mfma_f32_16x16x32_bf16 v[56:59], v[184:187], v[210:213], v[86:89]
	v_mfma_f32_16x16x32_bf16 v[86:89], v[188:191], v[214:217], v[56:59]
	v_mfma_f32_16x16x32_bf16 v[56:59], v[184:187], v[218:221], v[82:85]
	v_mfma_f32_16x16x32_bf16 v[26:29], v[192:195], v[200:203], v[26:29]
	v_mfma_f32_16x16x32_bf16 v[18:21], v[192:195], v[210:213], v[18:21]
	v_mfma_f32_16x16x32_bf16 v[82:85], v[188:191], v[222:225], v[56:59]
	v_mfma_f32_16x16x32_bf16 v[10:13], v[192:195], v[218:221], v[10:13]
	v_mfma_f32_16x16x32_bf16 v[56:59], v[184:187], v[226:229], v[64:67]
	v_mfma_f32_16x16x32_bf16 v[2:5], v[192:195], v[226:229], v[2:5]
	v_mfma_f32_16x16x32_bf16 v[26:29], v[196:199], v[204:207], v[26:29]
	v_mfma_f32_16x16x32_bf16 v[18:21], v[196:199], v[214:217], v[18:21]
	v_mfma_f32_16x16x32_bf16 v[10:13], v[196:199], v[222:225], v[10:13]
	v_mfma_f32_16x16x32_bf16 v[66:69], v[188:191], v[230:233], v[56:59]
	v_mfma_f32_16x16x32_bf16 v[2:5], v[196:199], v[230:233], v[2:5]
	s_barrier
	s_add_i32 s52, s52, 2
	s_add_u32 s28, s28, 0x200000
	s_addc_u32 s29, s29, 0
	s_add_u32 s84, s84, 0x820000
	s_addc_u32 s85, s85, 0
	s_cmp_gt_u32 s52, 13
	s_cbranch_scc0 .LBB0_155
	s_and_b64 vcc, exec, s[38:39]
	s_cbranch_vccz .LBB0_158
	s_barrier

; #define G8_STA(bufoff, ptr, sg, h) G8_STAGE1(bufoff, (ptr) + (h) * ((sg) ? hA1 : hA0), ((sg) ? voffA1 : voffA0), ((sg) ? r64A1 : r64A0))
; #define G8_LDA(dst, b, h) do { _Pragma("unroll") for (int m = 0; m < 4; ++m) _Pragma("unroll") for (int k = 0; k < 2; ++k) dst[m][k] = *(const LAS bf16x8*)(lds + G8_SA(b, h) + aoff + m * 2048 + k * 1024); } while (0)
; #define G8_LDB(dst, b, h) do { _Pragma("unroll") for (int n = 0; n < 2; ++n) _Pragma("unroll") for (int k = 0; k < 2; ++k) dst[n][k] = *(const LAS bf16x8*)(lds + G8_SB(b, h) + boff + n * 2048 + k * 1024); } while (0)
; #define G8_MMA(ai, bj, At, Bt) do { __builtin_amdgcn_s_setprio(1); _Pragma("unroll") for (int m = 0; m < 4; ++m) _Pragma("unroll") for (int n = 0; n < 2; ++n) _Pragma("unroll") for (int k = 0; k < 2; ++k) \
;         acc[ai][bj][m][n] = __builtin_amdgcn_mfma_f32_16x16x32_bf16(Bt[n][k], At[m][k], acc[ai][bj][m][n], 0, 0, 0); __builtin_amdgcn_s_setprio(0); } while (0)
; #define G8_BAR __builtin_amdgcn_s_barrier()
; template <class P>
; __device__ __forceinline__ void gemm_phase(LAS unsigned char* lds, const P& p, const int G, const int c) {
;     ...
;         const bool has_next = p.unit((ui + 1) * G + c, nxt);
;         const int nt = p.nt(cur);
;         const char* nA0 = has_next ? p.a_base(nxt, 0) - p.a_bias(0) : cA0; const char* nA1 = has_next ? p.a_base(nxt, S1) - p.a_bias(S1) : cA1;
;         const char* nB0 = has_next ? p.b_base(nxt, 0) - p.b_bias(0) : cB0; const char* nB1 = has_next ? p.b_base(nxt, S1) - p.b_bias(S1) : cB1;
;         for (int t = 0; t < nt; t += 2) {
;             const bool last = (t == nt - 2);
;             const bool sg1 = (NS > 1) && (t + 1 >= nt0);
;             const bool sg2 = (NS > 1) && !last && (t + 2 >= nt0);
;             const char* a1 = sg1 ? cA1 + (long)(t + 1 - nt0) * ksA1 : cA0 + (long)(t + 1) * ksA0;
;             const char* a2 = last ? nA0 : (sg2 ? cA1 + (long)(t + 2 - nt0) * ksA1 : cA0 + (long)(t + 2) * ksA0);
;             const char* b2 = last ? nB0 : (sg2 ? cB1 + (long)(t + 2 - nt0) * ksB1 : cB0 + (long)(t + 2) * ksB0);
;             const char* a3 = a2 + (sg2 ? ksA1 : ksA0); const char* b3 = b2 + (sg2 ? ksB1 : ksB0);
;             G8_LDB(B0, 0, 0); G8_LDB(B1, 0, 1); G8_SCHED; G8_LDA(At, 0, 0); G8_STA(G8_SA(1, 1), a1, sg1, 1);
;             G8_WAIT_V(8); G8_WAIT_L(0); G8_BAR; G8_MMA(0, 0, At, B0); G8_MMA(0, 1, At, B1); G8_BAR; G8_SCHED;
.LBB0_538:
	s_lshl_b64 s[18:19], s[18:19], 20
	s_add_u32 s90, s26, s18
	s_addc_u32 s91, s27, s19
	s_and_b64 s[6:7], s[6:7], exec
	s_cselect_b32 s18, s91, s93
	s_cselect_b32 s19, s90, s92
	s_add_u32 s28, s28, 0x40000
	s_addc_u32 s29, s29, 0
	v_lshl_add_u64 v[154:155], s[92:93], 0, v[152:153]
	s_mov_b32 s47, -2
	s_mov_b64 s[94:95], 0
	s_add_u32 s6, s92, s94
	s_addc_u32 s7, s93, s95
	s_add_u32 s6, s6, 0x10000
	s_addc_u32 s7, s7, 0
	s_add_i32 s65, 0, 0x10000
	s_cmp_eq_u32 s94, 0x30000
	s_cselect_b32 s7, s18, s7
	s_cselect_b32 s6, s19, s6
	v_add_u32_e32 v130, s65, v156
	s_cselect_b32 s51, s89, s29
	s_cselect_b32 s50, s88, s28
	s_add_i32 s34, 0, 0x14000
	ds_read_b128 v[160:163], v130
	ds_read_b128 v[164:167], v130 offset:1024
	ds_read_b128 v[168:171], v130 offset:2048
	ds_read_b128 v[172:175], v130 offset:3072
	v_add_u32_e32 v130, s34, v156
	ds_read_b128 v[176:179], v130
	ds_read_b128 v[180:183], v130 offset:1024
	ds_read_b128 v[184:187], v130 offset:2048
	ds_read_b128 v[188:191], v130 offset:3072
	v_lshl_add_u64 v[226:227], v[154:155], 0, s[94:95]
	s_mov_b64 s[54:55], 0xc000
	v_lshl_add_u64 v[228:229], v[226:227], 0, s[54:55]
	s_add_i32 m0, s11, 0xc000
	s_mov_b64 s[54:55], 0xe000
	ds_read_b128 v[192:195], v158
	ds_read_b128 v[196:199], v158 offset:1024
	ds_read_b128 v[200:203], v158 offset:2048
	ds_read_b128 v[204:207], v158 offset:3072
	ds_read_b128 v[210:213], v158 offset:4096
	ds_read_b128 v[214:217], v158 offset:5120
	ds_read_b128 v[218:221], v158 offset:6144
	ds_read_b128 v[222:225], v158 offset:7168
	global_load_lds_dwordx4 v[228:229], off
	v_lshl_add_u64 v[226:227], v[226:227], 0, s[54:55]
	s_add_i32 m0, s11, 0xe000
	s_nop 0
	global_load_lds_dwordx4 v[226:227], off
	s_waitcnt vmcnt(8)
	s_waitcnt lgkmcnt(0)
	s_barrier
	s_waitcnt lgkmcnt(0)
	v_mfma_f32_16x16x32_bf16 v[126:129], v[160:163], v[192:195], 0
	v_mfma_f32_16x16x32_bf16 v[122:125], v[168:171], v[192:195], 0
	v_mfma_f32_16x16x32_bf16 v[118:121], v[160:163], v[200:203], 0
	v_mfma_f32_16x16x32_bf16 v[114:117], v[168:171], v[200:203], 0
	v_mfma_f32_16x16x32_bf16 v[102:105], v[160:163], v[210:213], 0
	v_mfma_f32_16x16x32_bf16 v[98:101], v[168:171], v[210:213], 0
	v_mfma_f32_16x16x32_bf16 v[86:89], v[160:163], v[218:221], 0
	v_mfma_f32_16x16x32_bf16 v[82:85], v[168:171], v[218:221], 0
	v_mfma_f32_16x16x32_bf16 v[126:129], v[164:167], v[196:199], v[126:129]
	v_mfma_f32_16x16x32_bf16 v[122:125], v[172:175], v[196:199], v[122:125]
	v_mfma_f32_16x16x32_bf16 v[118:121], v[164:167], v[204:207], v[118:121]
	v_mfma_f32_16x16x32_bf16 v[114:117], v[172:175], v[204:207], v[114:117]
	v_mfma_f32_16x16x32_bf16 v[102:105], v[164:167], v[214:217], v[102:105]
	v_mfma_f32_16x16x32_bf16 v[98:101], v[172:175], v[214:217], v[98:101]
	v_mfma_f32_16x16x32_bf16 v[86:89], v[164:167], v[222:225], v[86:89]
	v_mfma_f32_16x16x32_bf16 v[82:85], v[172:175], v[222:225], v[82:85]
	v_mfma_f32_16x16x32_bf16 v[110:113], v[176:179], v[192:195], 0
	v_mfma_f32_16x16x32_bf16 v[106:109], v[184:187], v[192:195], 0
	v_mfma_f32_16x16x32_bf16 v[94:97], v[176:179], v[200:203], 0
	v_mfma_f32_16x16x32_bf16 v[90:93], v[184:187], v[200:203], 0
	v_mfma_f32_16x16x32_bf16 v[78:81], v[176:179], v[210:213], 0
	v_mfma_f32_16x16x32_bf16 v[74:77], v[184:187], v[210:213], 0
	v_mfma_f32_16x16x32_bf16 v[70:73], v[176:179], v[218:221], 0
	v_mfma_f32_16x16x32_bf16 v[66:69], v[184:187], v[218:221], 0
	v_mfma_f32_16x16x32_bf16 v[110:113], v[180:183], v[196:199], v[110:113]
	v_mfma_f32_16x16x32_bf16 v[106:109], v[188:191], v[196:199], v[106:109]
	v_mfma_f32_16x16x32_bf16 v[94:97], v[180:183], v[204:207], v[94:97]
	v_mfma_f32_16x16x32_bf16 v[90:93], v[188:191], v[204:207], v[90:93]
	v_mfma_f32_16x16x32_bf16 v[78:81], v[180:183], v[214:217], v[78:81]
	v_mfma_f32_16x16x32_bf16 v[74:77], v[188:191], v[214:217], v[74:77]
	v_mfma_f32_16x16x32_bf16 v[70:73], v[180:183], v[222:225], v[70:73]
	v_mfma_f32_16x16x32_bf16 v[66:69], v[188:191], v[222:225], v[66:69]
	s_barrier
; #define G8_STA(bufoff, ptr, sg, h) G8_STAGE1(bufoff, (ptr) + (h) * ((sg) ? hA1 : hA0), ((sg) ? voffA1 : voffA0), ((sg) ? r64A1 : r64A0))
; #define G8_STB(bufoff, ptr, sg, h) G8_STAGE1(bufoff, (ptr) + (h) * ((sg) ? hB1 : hB0), ((sg) ? voffB1 : voffB0), ((sg) ? r64B1 : r64B0))
; #define G8_LDA(dst, b, h) do { _Pragma("unroll") for (int m = 0; m < 4; ++m) _Pragma("unroll") for (int k = 0; k < 2; ++k) dst[m][k] = *(const LAS bf16x8*)(lds + G8_SA(b, h) + aoff + m * 2048 + k * 1024); } while (0)
; #define G8_MMA(ai, bj, At, Bt) do { __builtin_amdgcn_s_setprio(1); _Pragma("unroll") for (int m = 0; m < 4; ++m) _Pragma("unroll") for (int n = 0; n < 2; ++n) _Pragma("unroll") for (int k = 0; k < 2; ++k) \
;         acc[ai][bj][m][n] = __builtin_amdgcn_mfma_f32_16x16x32_bf16(Bt[n][k], At[m][k], acc[ai][bj][m][n], 0, 0, 0); __builtin_amdgcn_s_setprio(0); } while (0)
; #define G8_WAIT_V(n) asm volatile("s_waitcnt vmcnt(" #n ")" ::: "memory")
; #define G8_WAIT_L(n) asm volatile("s_waitcnt lgkmcnt(" #n ")" ::: "memory")
; #define G8_BAR __builtin_amdgcn_s_barrier()
; #define G8_SCHED __builtin_amdgcn_sched_barrier(0)
; template <class P>
; __device__ __forceinline__ void gemm_phase(LAS unsigned char* lds, const P& p, const int G, const int c) {
;     ...
;             G8_LDA(At, 0, 1); G8_STB(G8_SB(0, 0), b2, sg2, 0); G8_STB(G8_SB(0, 1), b2, sg2, 1); G8_STA(G8_SA(0, 0), a2, sg2, 0);
;             G8_WAIT_V(8); G8_WAIT_L(0); G8_BAR; G8_MMA(1, 0, At, B0); G8_MMA(1, 1, At, B1); G8_BAR; G8_SCHED;
	s_add_i32 s20, s65, s10
	v_lshl_add_u64 v[226:227], s[50:51], 0, v[132:133]
	s_mov_b32 m0, s20
	ds_read_b128 v[192:195], v158 offset:16384
	ds_read_b128 v[196:199], v158 offset:17408
	ds_read_b128 v[200:203], v158 offset:18432
	ds_read_b128 v[204:207], v158 offset:19456
	ds_read_b128 v[210:213], v158 offset:20480
	ds_read_b128 v[214:217], v158 offset:21504
	ds_read_b128 v[218:221], v158 offset:22528
	ds_read_b128 v[222:225], v158 offset:23552
	global_load_lds_dwordx4 v[226:227], off
	v_lshl_add_u64 v[228:229], v[226:227], 0, s[22:23]
	s_add_i32 m0, s20, 0x2000
	s_add_i32 s20, s34, s10
	global_load_lds_dwordx4 v[228:229], off
	v_lshl_add_u64 v[228:229], v[226:227], 0, s[36:37]
	s_mov_b32 m0, s20
	s_nop 0
	global_load_lds_dwordx4 v[228:229], off
	v_lshl_add_u64 v[228:229], v[226:227], 0, s[38:39]
	s_add_i32 m0, s20, 0x2000
	s_nop 0
	global_load_lds_dwordx4 v[228:229], off
	v_lshl_add_u64 v[228:229], s[6:7], 0, v[134:135]
	s_mov_b32 m0, s11
	v_lshl_add_u64 v[230:231], v[228:229], 0, s[22:23]
	global_load_lds_dwordx4 v[228:229], off
	s_mov_b32 m0, s14
	s_nop 0
	global_load_lds_dwordx4 v[230:231], off
	s_waitcnt vmcnt(8)
	s_waitcnt lgkmcnt(0)
	s_barrier
	s_waitcnt lgkmcnt(0)
	v_mfma_f32_16x16x32_bf16 v[62:65], v[160:163], v[192:195], 0
	v_mfma_f32_16x16x32_bf16 v[58:61], v[168:171], v[192:195], 0
	v_mfma_f32_16x16x32_bf16 v[54:57], v[160:163], v[200:203], 0
	v_mfma_f32_16x16x32_bf16 v[50:53], v[168:171], v[200:203], 0
	v_mfma_f32_16x16x32_bf16 v[38:41], v[160:163], v[210:213], 0
	v_mfma_f32_16x16x32_bf16 v[34:37], v[168:171], v[210:213], 0
	v_mfma_f32_16x16x32_bf16 v[22:25], v[160:163], v[218:221], 0
	v_mfma_f32_16x16x32_bf16 v[18:21], v[168:171], v[218:221], 0
	v_mfma_f32_16x16x32_bf16 v[62:65], v[164:167], v[196:199], v[62:65]
	v_mfma_f32_16x16x32_bf16 v[58:61], v[172:175], v[196:199], v[58:61]
	v_mfma_f32_16x16x32_bf16 v[54:57], v[164:167], v[204:207], v[54:57]
	v_mfma_f32_16x16x32_bf16 v[50:53], v[172:175], v[204:207], v[50:53]
	v_mfma_f32_16x16x32_bf16 v[38:41], v[164:167], v[214:217], v[38:41]
	v_mfma_f32_16x16x32_bf16 v[34:37], v[172:175], v[214:217], v[34:37]
	v_mfma_f32_16x16x32_bf16 v[22:25], v[164:167], v[222:225], v[22:25]
	v_mfma_f32_16x16x32_bf16 v[18:21], v[172:175], v[222:225], v[18:21]
	v_mfma_f32_16x16x32_bf16 v[46:49], v[176:179], v[192:195], 0
	v_mfma_f32_16x16x32_bf16 v[42:45], v[184:187], v[192:195], 0
	v_mfma_f32_16x16x32_bf16 v[30:33], v[176:179], v[200:203], 0
	v_mfma_f32_16x16x32_bf16 v[26:29], v[184:187], v[200:203], 0
	v_mfma_f32_16x16x32_bf16 v[14:17], v[176:179], v[210:213], 0
	v_mfma_f32_16x16x32_bf16 v[10:13], v[184:187], v[210:213], 0
	v_mfma_f32_16x16x32_bf16 v[6:9], v[176:179], v[218:221], 0
	v_mfma_f32_16x16x32_bf16 v[2:5], v[184:187], v[218:221], 0
	v_mfma_f32_16x16x32_bf16 v[46:49], v[180:183], v[196:199], v[46:49]
	v_mfma_f32_16x16x32_bf16 v[42:45], v[188:191], v[196:199], v[42:45]
	v_mfma_f32_16x16x32_bf16 v[30:33], v[180:183], v[204:207], v[30:33]
	v_mfma_f32_16x16x32_bf16 v[26:29], v[188:191], v[204:207], v[26:29]
	v_mfma_f32_16x16x32_bf16 v[14:17], v[180:183], v[214:217], v[14:17]
	v_mfma_f32_16x16x32_bf16 v[10:13], v[188:191], v[214:217], v[10:13]
	v_mfma_f32_16x16x32_bf16 v[6:9], v[180:183], v[222:225], v[6:9]
	v_mfma_f32_16x16x32_bf16 v[2:5], v[188:191], v[222:225], v[2:5]
	s_branch .Lmid_539

; #define G8_STA(bufoff, ptr, sg, h) G8_STAGE1(bufoff, (ptr) + (h) * ((sg) ? hA1 : hA0), ((sg) ? voffA1 : voffA0), ((sg) ? r64A1 : r64A0))
; #define G8_STB(bufoff, ptr, sg, h) G8_STAGE1(bufoff, (ptr) + (h) * ((sg) ? hB1 : hB0), ((sg) ? voffB1 : voffB0), ((sg) ? r64B1 : r64B0))
; #define G8_LDA(dst, b, h) do { _Pragma("unroll") for (int m = 0; m < 4; ++m) _Pragma("unroll") for (int k = 0; k < 2; ++k) dst[m][k] = *(const LAS bf16x8*)(lds + G8_SA(b, h) + aoff + m * 2048 + k * 1024); } while (0)
; #define G8_LDB(dst, b, h) do { _Pragma("unroll") for (int n = 0; n < 2; ++n) _Pragma("unroll") for (int k = 0; k < 2; ++k) dst[n][k] = *(const LAS bf16x8*)(lds + G8_SB(b, h) + boff + n * 2048 + k * 1024); } while (0)
; #define G8_MMA(ai, bj, At, Bt) do { __builtin_amdgcn_s_setprio(1); _Pragma("unroll") for (int m = 0; m < 4; ++m) _Pragma("unroll") for (int n = 0; n < 2; ++n) _Pragma("unroll") for (int k = 0; k < 2; ++k) \
;         acc[ai][bj][m][n] = __builtin_amdgcn_mfma_f32_16x16x32_bf16(Bt[n][k], At[m][k], acc[ai][bj][m][n], 0, 0, 0); __builtin_amdgcn_s_setprio(0); } while (0)
; #define G8_WAIT_V(n) asm volatile("s_waitcnt vmcnt(" #n ")" ::: "memory")
; #define G8_WAIT_L(n) asm volatile("s_waitcnt lgkmcnt(" #n ")" ::: "memory")
; #define G8_BAR __builtin_amdgcn_s_barrier()
; #define G8_SCHED __builtin_amdgcn_sched_barrier(0)
; template <class P>
; __device__ __forceinline__ void gemm_phase(LAS unsigned char* lds, const P& p, const int G, const int c) {
;     ...
;             G8_LDB(B0, 1, 0); G8_LDB(B1, 1, 1); G8_SCHED; G8_LDA(At, 1, 0); G8_STA(G8_SA(0, 1), a2, sg2, 1);
;             G8_WAIT_V(8); G8_WAIT_L(0); G8_BAR; G8_MMA(0, 0, At, B0); G8_MMA(0, 1, At, B1); G8_BAR; G8_SCHED;
;             G8_LDA(At, 1, 1); G8_STB(G8_SB(1, 0), b3, sg2, 0); G8_STB(G8_SB(1, 1), b3, sg2, 1); G8_STA(G8_SA(1, 0), a3, sg2, 0);
;             G8_WAIT_V(8); G8_WAIT_L(0); G8_BAR; G8_MMA(1, 0, At, B0); G8_MMA(1, 1, At, B1); G8_BAR; G8_SCHED;
;         }
.Lmid_539:
	s_barrier
	s_add_i32 s35, 0, 0x18000
	v_add_u32_e32 v130, s35, v156
	s_add_i32 s20, 0, 0x1c000
	ds_read_b128 v[160:163], v130
	ds_read_b128 v[164:167], v130 offset:1024
	ds_read_b128 v[168:171], v130 offset:2048
	ds_read_b128 v[172:175], v130 offset:3072
	v_add_u32_e32 v130, s20, v156
	ds_read_b128 v[176:179], v130
	ds_read_b128 v[180:183], v130 offset:1024
	ds_read_b128 v[184:187], v130 offset:2048
	ds_read_b128 v[188:191], v130 offset:3072
	s_mov_b32 m0, s15
	v_lshl_add_u64 v[230:231], v[228:229], 0, s[36:37]
	ds_read_b128 v[192:195], v158 offset:32768
	ds_read_b128 v[196:199], v158 offset:33792
	ds_read_b128 v[200:203], v158 offset:34816
	ds_read_b128 v[204:207], v158 offset:35840
	ds_read_b128 v[210:213], v158 offset:36864
	ds_read_b128 v[214:217], v158 offset:37888
	ds_read_b128 v[218:221], v158 offset:38912
	ds_read_b128 v[222:225], v158 offset:39936
	global_load_lds_dwordx4 v[230:231], off
	v_lshl_add_u64 v[230:231], v[228:229], 0, s[38:39]
	s_mov_b32 m0, s16
	s_nop 0
	global_load_lds_dwordx4 v[230:231], off
	s_waitcnt vmcnt(8)
	s_waitcnt lgkmcnt(0)
	s_barrier
	s_waitcnt lgkmcnt(0)
	v_mfma_f32_16x16x32_bf16 v[126:129], v[160:163], v[192:195], v[126:129]
	v_mfma_f32_16x16x32_bf16 v[122:125], v[168:171], v[192:195], v[122:125]
	v_mfma_f32_16x16x32_bf16 v[118:121], v[160:163], v[200:203], v[118:121]
	v_mfma_f32_16x16x32_bf16 v[114:117], v[168:171], v[200:203], v[114:117]
	v_mfma_f32_16x16x32_bf16 v[102:105], v[160:163], v[210:213], v[102:105]
	v_mfma_f32_16x16x32_bf16 v[98:101], v[168:171], v[210:213], v[98:101]
	v_mfma_f32_16x16x32_bf16 v[86:89], v[160:163], v[218:221], v[86:89]
	v_mfma_f32_16x16x32_bf16 v[82:85], v[168:171], v[218:221], v[82:85]
	v_mfma_f32_16x16x32_bf16 v[126:129], v[164:167], v[196:199], v[126:129]
	v_mfma_f32_16x16x32_bf16 v[122:125], v[172:175], v[196:199], v[122:125]
	v_mfma_f32_16x16x32_bf16 v[118:121], v[164:167], v[204:207], v[118:121]
	v_mfma_f32_16x16x32_bf16 v[114:117], v[172:175], v[204:207], v[114:117]
	v_mfma_f32_16x16x32_bf16 v[102:105], v[164:167], v[214:217], v[102:105]
	v_mfma_f32_16x16x32_bf16 v[98:101], v[172:175], v[214:217], v[98:101]
	v_mfma_f32_16x16x32_bf16 v[86:89], v[164:167], v[222:225], v[86:89]
	v_mfma_f32_16x16x32_bf16 v[82:85], v[172:175], v[222:225], v[82:85]
	v_mfma_f32_16x16x32_bf16 v[110:113], v[176:179], v[192:195], v[110:113]
	v_mfma_f32_16x16x32_bf16 v[106:109], v[184:187], v[192:195], v[106:109]
	v_mfma_f32_16x16x32_bf16 v[94:97], v[176:179], v[200:203], v[94:97]
	v_mfma_f32_16x16x32_bf16 v[90:93], v[184:187], v[200:203], v[90:93]
	v_mfma_f32_16x16x32_bf16 v[78:81], v[176:179], v[210:213], v[78:81]
	v_mfma_f32_16x16x32_bf16 v[74:77], v[184:187], v[210:213], v[74:77]
	v_mfma_f32_16x16x32_bf16 v[70:73], v[176:179], v[218:221], v[70:73]
	v_mfma_f32_16x16x32_bf16 v[66:69], v[184:187], v[218:221], v[66:69]
	v_mfma_f32_16x16x32_bf16 v[110:113], v[180:183], v[196:199], v[110:113]
	v_mfma_f32_16x16x32_bf16 v[106:109], v[188:191], v[196:199], v[106:109]
	v_mfma_f32_16x16x32_bf16 v[94:97], v[180:183], v[204:207], v[94:97]
	v_mfma_f32_16x16x32_bf16 v[90:93], v[188:191], v[204:207], v[90:93]
	v_mfma_f32_16x16x32_bf16 v[78:81], v[180:183], v[214:217], v[78:81]
	v_mfma_f32_16x16x32_bf16 v[74:77], v[188:191], v[214:217], v[74:77]
	v_mfma_f32_16x16x32_bf16 v[70:73], v[180:183], v[222:225], v[70:73]
	v_mfma_f32_16x16x32_bf16 v[66:69], v[188:191], v[222:225], v[66:69]
	s_barrier
	s_add_i32 s6, s35, s10
	v_lshl_add_u64 v[230:231], v[226:227], 0, s[40:41]
	s_mov_b32 m0, s6
	ds_read_b128 v[192:195], v158 offset:49152
	ds_read_b128 v[196:199], v158 offset:50176
	ds_read_b128 v[200:203], v158 offset:51200
	ds_read_b128 v[204:207], v158 offset:52224
	ds_read_b128 v[210:213], v158 offset:53248
	ds_read_b128 v[214:217], v158 offset:54272
	ds_read_b128 v[218:221], v158 offset:55296
	ds_read_b128 v[222:225], v158 offset:56320
	global_load_lds_dwordx4 v[230:231], off
	v_lshl_add_u64 v[230:231], v[226:227], 0, s[42:43]
	s_add_i32 m0, s6, 0x2000
	s_add_i32 s6, s20, s10
	global_load_lds_dwordx4 v[230:231], off
	v_lshl_add_u64 v[230:231], v[226:227], 0, s[48:49]
	s_mov_b32 m0, s6
	v_lshl_add_u64 v[226:227], v[226:227], 0, s[52:53]
	global_load_lds_dwordx4 v[230:231], off
	s_add_i32 m0, s6, 0x2000
	s_nop 0
	global_load_lds_dwordx4 v[226:227], off
	v_lshl_add_u64 v[226:227], v[228:229], 0, s[8:9]
	s_mov_b32 m0, s24
	s_nop 0
	global_load_lds_dwordx4 v[226:227], off
	v_lshl_add_u64 v[226:227], v[228:229], 0, s[44:45]
	s_mov_b32 m0, s25
	s_nop 0
	global_load_lds_dwordx4 v[226:227], off
	s_waitcnt vmcnt(8)
	s_waitcnt lgkmcnt(0)
	s_barrier
	s_waitcnt lgkmcnt(0)
	v_mfma_f32_16x16x32_bf16 v[62:65], v[160:163], v[192:195], v[62:65]
	v_mfma_f32_16x16x32_bf16 v[58:61], v[168:171], v[192:195], v[58:61]
	v_mfma_f32_16x16x32_bf16 v[54:57], v[160:163], v[200:203], v[54:57]
	v_mfma_f32_16x16x32_bf16 v[50:53], v[168:171], v[200:203], v[50:53]
	v_mfma_f32_16x16x32_bf16 v[38:41], v[160:163], v[210:213], v[38:41]
	v_mfma_f32_16x16x32_bf16 v[34:37], v[168:171], v[210:213], v[34:37]
	v_mfma_f32_16x16x32_bf16 v[22:25], v[160:163], v[218:221], v[22:25]
	v_mfma_f32_16x16x32_bf16 v[18:21], v[168:171], v[218:221], v[18:21]
	v_mfma_f32_16x16x32_bf16 v[62:65], v[164:167], v[196:199], v[62:65]
	v_mfma_f32_16x16x32_bf16 v[58:61], v[172:175], v[196:199], v[58:61]
	v_mfma_f32_16x16x32_bf16 v[54:57], v[164:167], v[204:207], v[54:57]
	v_mfma_f32_16x16x32_bf16 v[50:53], v[172:175], v[204:207], v[50:53]
	v_mfma_f32_16x16x32_bf16 v[38:41], v[164:167], v[214:217], v[38:41]
	v_mfma_f32_16x16x32_bf16 v[34:37], v[172:175], v[214:217], v[34:37]
	v_mfma_f32_16x16x32_bf16 v[22:25], v[164:167], v[222:225], v[22:25]
	v_mfma_f32_16x16x32_bf16 v[18:21], v[172:175], v[222:225], v[18:21]
	v_mfma_f32_16x16x32_bf16 v[46:49], v[176:179], v[192:195], v[46:49]
	v_mfma_f32_16x16x32_bf16 v[42:45], v[184:187], v[192:195], v[42:45]
	v_mfma_f32_16x16x32_bf16 v[30:33], v[176:179], v[200:203], v[30:33]
	v_mfma_f32_16x16x32_bf16 v[26:29], v[184:187], v[200:203], v[26:29]
	v_mfma_f32_16x16x32_bf16 v[14:17], v[176:179], v[210:213], v[14:17]
	v_mfma_f32_16x16x32_bf16 v[10:13], v[184:187], v[210:213], v[10:13]
	v_mfma_f32_16x16x32_bf16 v[6:9], v[176:179], v[218:221], v[6:9]
	v_mfma_f32_16x16x32_bf16 v[2:5], v[184:187], v[218:221], v[2:5]
	v_mfma_f32_16x16x32_bf16 v[46:49], v[180:183], v[196:199], v[46:49]
	v_mfma_f32_16x16x32_bf16 v[42:45], v[188:191], v[196:199], v[42:45]
	v_mfma_f32_16x16x32_bf16 v[30:33], v[180:183], v[204:207], v[30:33]
	v_mfma_f32_16x16x32_bf16 v[26:29], v[188:191], v[204:207], v[26:29]
	v_mfma_f32_16x16x32_bf16 v[14:17], v[180:183], v[214:217], v[14:17]
	v_mfma_f32_16x16x32_bf16 v[10:13], v[188:191], v[214:217], v[10:13]
	v_mfma_f32_16x16x32_bf16 v[6:9], v[180:183], v[222:225], v[6:9]
	v_mfma_f32_16x16x32_bf16 v[2:5], v[188:191], v[222:225], v[2:5]
	s_barrier
	s_add_i32 s47, s47, 2
	s_add_u32 s28, s28, 0x40000
	s_addc_u32 s29, s29, 0
	s_add_u32 s94, s94, 0x10000
	s_addc_u32 s95, s95, 0
	s_cmp_gt_u32 s47, 5
	s_cbranch_scc0 .LBB0_539
	s_and_b64 vcc, exec, s[86:87]
	s_cbranch_vccz .LBB0_542
	s_barrier

; #define G8_STA(bufoff, ptr, sg, h) G8_STAGE1(bufoff, (ptr) + (h) * ((sg) ? hA1 : hA0), ((sg) ? voffA1 : voffA0), ((sg) ? r64A1 : r64A0))
; #define G8_LDA(dst, b, h) do { _Pragma("unroll") for (int m = 0; m < 4; ++m) _Pragma("unroll") for (int k = 0; k < 2; ++k) dst[m][k] = *(const LAS bf16x8*)(lds + G8_SA(b, h) + aoff + m * 2048 + k * 1024); } while (0)
; #define G8_LDB(dst, b, h) do { _Pragma("unroll") for (int n = 0; n < 2; ++n) _Pragma("unroll") for (int k = 0; k < 2; ++k) dst[n][k] = *(const LAS bf16x8*)(lds + G8_SB(b, h) + boff + n * 2048 + k * 1024); } while (0)
; #define G8_MMA(ai, bj, At, Bt) do { __builtin_amdgcn_s_setprio(1); _Pragma("unroll") for (int m = 0; m < 4; ++m) _Pragma("unroll") for (int n = 0; n < 2; ++n) _Pragma("unroll") for (int k = 0; k < 2; ++k) \
;         acc[ai][bj][m][n] = __builtin_amdgcn_mfma_f32_16x16x32_bf16(Bt[n][k], At[m][k], acc[ai][bj][m][n], 0, 0, 0); __builtin_amdgcn_s_setprio(0); } while (0)
; #define G8_BAR __builtin_amdgcn_s_barrier()
; template <class P>
; __device__ __forceinline__ void gemm_phase(LAS unsigned char* lds, const P& p, const int G, const int c) {
;     ...
;         const bool has_next = p.unit((ui + 1) * G + c, nxt);
;         const int nt = p.nt(cur);
;         const char* nA0 = has_next ? p.a_base(nxt, 0) - p.a_bias(0) : cA0; const char* nA1 = has_next ? p.a_base(nxt, S1) - p.a_bias(S1) : cA1;
;         const char* nB0 = has_next ? p.b_base(nxt, 0) - p.b_bias(0) : cB0; const char* nB1 = has_next ? p.b_base(nxt, S1) - p.b_bias(S1) : cB1;
;         for (int t = 0; t < nt; t += 2) {
;             const bool last = (t == nt - 2);
;             const bool sg1 = (NS > 1) && (t + 1 >= nt0);
;             const bool sg2 = (NS > 1) && !last && (t + 2 >= nt0);
;             const char* a1 = sg1 ? cA1 + (long)(t + 1 - nt0) * ksA1 : cA0 + (long)(t + 1) * ksA0;
;             const char* a2 = last ? nA0 : (sg2 ? cA1 + (long)(t + 2 - nt0) * ksA1 : cA0 + (long)(t + 2) * ksA0);
;             const char* b2 = last ? nB0 : (sg2 ? cB1 + (long)(t + 2 - nt0) * ksB1 : cB0 + (long)(t + 2) * ksB0);
;             const char* a3 = a2 + (sg2 ? ksA1 : ksA0); const char* b3 = b2 + (sg2 ? ksB1 : ksB0);
;             G8_LDB(B0, 0, 0); G8_LDB(B1, 0, 1); G8_SCHED; G8_LDA(At, 0, 0); G8_STA(G8_SA(1, 1), a1, sg1, 1);
;             G8_WAIT_V(8); G8_WAIT_L(0); G8_BAR; G8_MMA(0, 0, At, B0); G8_MMA(0, 1, At, B1); G8_BAR; G8_SCHED;
.LBB0_706:
	s_ashr_i32 s61, s60, 31
	s_lshl_b64 s[18:19], s[60:61], 13
	s_add_u32 s68, s4, s18
	s_addc_u32 s69, s5, s19
	s_and_b64 s[18:19], s[58:59], exec
	s_cselect_b32 s18, s69, s75
	s_cselect_b32 s19, s68, s74
	s_ashr_i32 s63, s62, 31
	s_lshl_b64 s[64:65], s[62:63], 15
	s_add_u32 s70, s2, s64
	s_addc_u32 s71, s3, s65
	s_and_b64 s[64:65], s[58:59], exec
	s_cselect_b32 s61, s71, s29
	s_cselect_b32 s63, s70, s28
	s_add_u32 s28, s28, 0x80000
	s_addc_u32 s29, s29, 0
	v_lshl_add_u64 v[66:67], s[74:75], 0, v[212:213]
	s_mov_b32 s64, -2
	s_mov_b64 s[76:77], 0
	ds_read_b128 v[68:71], v230
	ds_read_b128 v[72:75], v230 offset:1024
	ds_read_b128 v[76:79], v230 offset:2048
	ds_read_b128 v[138:141], v230 offset:3072
	ds_read_b128 v[142:145], v231
	ds_read_b128 v[154:157], v231 offset:1024
	ds_read_b128 v[158:161], v231 offset:2048
	ds_read_b128 v[162:165], v231 offset:3072
	s_add_u32 s65, s74, s76
	s_addc_u32 s66, s75, s77
	s_add_u32 s65, s65, 0x800000
	s_addc_u32 s66, s66, 0
	s_cmp_eq_u32 s76, 0x7800000
	s_cselect_b32 s67, s18, s66
	s_cselect_b32 s66, s19, s65
	s_cselect_b32 s79, s61, s29
	s_cselect_b32 s78, s63, s28
	v_lshl_add_u64 v[80:81], v[66:67], 0, s[76:77]
	s_mov_b64 s[80:81], 0x401000
	v_lshl_add_u64 v[198:199], v[80:81], 0, s[80:81]
	s_add_i32 m0, s25, 0xc000
	ds_read_b128 v[166:169], v232
	ds_read_b128 v[170:173], v232 offset:1024
	ds_read_b128 v[174:177], v232 offset:2048
	ds_read_b128 v[178:181], v232 offset:3072
	ds_read_b128 v[182:185], v232 offset:4096
	ds_read_b128 v[186:189], v232 offset:5120
	ds_read_b128 v[190:193], v232 offset:6144
	ds_read_b128 v[194:197], v232 offset:7168
	global_load_lds_dwordx4 v[198:199], off
	v_lshl_add_u64 v[80:81], v[80:81], 0, s[54:55]
	s_add_i32 m0, s25, 0xe000
	s_nop 0
	global_load_lds_dwordx4 v[80:81], off
	s_waitcnt vmcnt(8)
	s_waitcnt lgkmcnt(0)
	s_barrier
	s_waitcnt lgkmcnt(0)
	v_mfma_f32_16x16x32_bf16 v[150:153], v[68:71], v[166:169], 0
	v_mfma_f32_16x16x32_bf16 v[146:149], v[76:79], v[166:169], 0
	v_mfma_f32_16x16x32_bf16 v[126:129], v[68:71], v[174:177], 0
	v_mfma_f32_16x16x32_bf16 v[122:125], v[76:79], v[174:177], 0
	v_mfma_f32_16x16x32_bf16 v[110:113], v[68:71], v[182:185], 0
	v_mfma_f32_16x16x32_bf16 v[106:109], v[76:79], v[182:185], 0
	v_mfma_f32_16x16x32_bf16 v[94:97], v[68:71], v[190:193], 0
	v_mfma_f32_16x16x32_bf16 v[90:93], v[76:79], v[190:193], 0
	v_mfma_f32_16x16x32_bf16 v[150:153], v[72:75], v[170:173], v[150:153]
	v_mfma_f32_16x16x32_bf16 v[146:149], v[138:141], v[170:173], v[146:149]
	v_mfma_f32_16x16x32_bf16 v[126:129], v[72:75], v[178:181], v[126:129]
	v_mfma_f32_16x16x32_bf16 v[122:125], v[138:141], v[178:181], v[122:125]
	v_mfma_f32_16x16x32_bf16 v[110:113], v[72:75], v[186:189], v[110:113]
	v_mfma_f32_16x16x32_bf16 v[106:109], v[138:141], v[186:189], v[106:109]
	v_mfma_f32_16x16x32_bf16 v[94:97], v[72:75], v[194:197], v[94:97]
	v_mfma_f32_16x16x32_bf16 v[90:93], v[138:141], v[194:197], v[90:93]
	v_mfma_f32_16x16x32_bf16 v[134:137], v[142:145], v[166:169], 0
	v_mfma_f32_16x16x32_bf16 v[130:133], v[158:161], v[166:169], 0
	v_mfma_f32_16x16x32_bf16 v[118:121], v[142:145], v[174:177], 0
	v_mfma_f32_16x16x32_bf16 v[114:117], v[158:161], v[174:177], 0
	v_mfma_f32_16x16x32_bf16 v[102:105], v[142:145], v[182:185], 0
	v_mfma_f32_16x16x32_bf16 v[98:101], v[158:161], v[182:185], 0
	v_mfma_f32_16x16x32_bf16 v[86:89], v[142:145], v[190:193], 0
	v_mfma_f32_16x16x32_bf16 v[80:83], v[158:161], v[190:193], 0
	v_mfma_f32_16x16x32_bf16 v[134:137], v[154:157], v[170:173], v[134:137]
	v_mfma_f32_16x16x32_bf16 v[130:133], v[162:165], v[170:173], v[130:133]
	v_mfma_f32_16x16x32_bf16 v[118:121], v[154:157], v[178:181], v[118:121]
	v_mfma_f32_16x16x32_bf16 v[114:117], v[162:165], v[178:181], v[114:117]
	v_mfma_f32_16x16x32_bf16 v[102:105], v[154:157], v[186:189], v[102:105]
	v_mfma_f32_16x16x32_bf16 v[98:101], v[162:165], v[186:189], v[98:101]
	v_mfma_f32_16x16x32_bf16 v[86:89], v[154:157], v[194:197], v[86:89]
	v_mfma_f32_16x16x32_bf16 v[80:83], v[162:165], v[194:197], v[80:83]
	s_barrier
; #define G8_STA(bufoff, ptr, sg, h) G8_STAGE1(bufoff, (ptr) + (h) * ((sg) ? hA1 : hA0), ((sg) ? voffA1 : voffA0), ((sg) ? r64A1 : r64A0))
; #define G8_STB(bufoff, ptr, sg, h) G8_STAGE1(bufoff, (ptr) + (h) * ((sg) ? hB1 : hB0), ((sg) ? voffB1 : voffB0), ((sg) ? r64B1 : r64B0))
; #define G8_LDA(dst, b, h) do { _Pragma("unroll") for (int m = 0; m < 4; ++m) _Pragma("unroll") for (int k = 0; k < 2; ++k) dst[m][k] = *(const LAS bf16x8*)(lds + G8_SA(b, h) + aoff + m * 2048 + k * 1024); } while (0)
; #define G8_MMA(ai, bj, At, Bt) do { __builtin_amdgcn_s_setprio(1); _Pragma("unroll") for (int m = 0; m < 4; ++m) _Pragma("unroll") for (int n = 0; n < 2; ++n) _Pragma("unroll") for (int k = 0; k < 2; ++k) \
;         acc[ai][bj][m][n] = __builtin_amdgcn_mfma_f32_16x16x32_bf16(Bt[n][k], At[m][k], acc[ai][bj][m][n], 0, 0, 0); __builtin_amdgcn_s_setprio(0); } while (0)
; #define G8_WAIT_V(n) asm volatile("s_waitcnt vmcnt(" #n ")" ::: "memory")
; #define G8_WAIT_L(n) asm volatile("s_waitcnt lgkmcnt(" #n ")" ::: "memory")
; #define G8_BAR __builtin_amdgcn_s_barrier()
; #define G8_SCHED __builtin_amdgcn_sched_barrier(0)
; template <class P>
; __device__ __forceinline__ void gemm_phase(LAS unsigned char* lds, const P& p, const int G, const int c) {
;     ...
;             G8_LDA(At, 0, 1); G8_STB(G8_SB(0, 0), b2, sg2, 0); G8_STB(G8_SB(0, 1), b2, sg2, 1); G8_STA(G8_SA(0, 0), a2, sg2, 0);
;             G8_WAIT_V(8); G8_WAIT_L(0); G8_BAR; G8_MMA(1, 0, At, B0); G8_MMA(1, 1, At, B1); G8_BAR; G8_SCHED;
	s_add_i32 s65, s50, s24
	v_lshl_add_u64 v[198:199], s[78:79], 0, v[202:203]
	s_mov_b32 m0, s65
	ds_read_b128 v[166:169], v232 offset:16384
	ds_read_b128 v[170:173], v232 offset:17408
	ds_read_b128 v[174:177], v232 offset:18432
	ds_read_b128 v[178:181], v232 offset:19456
	ds_read_b128 v[182:185], v232 offset:20480
	ds_read_b128 v[186:189], v232 offset:21504
	ds_read_b128 v[190:193], v232 offset:22528
	ds_read_b128 v[194:197], v232 offset:23552
	global_load_lds_dwordx4 v[198:199], off
	v_lshl_add_u64 v[84:85], v[198:199], 0, s[6:7]
	s_add_i32 m0, s65, 0x2000
	s_add_i32 s65, s51, s24
	global_load_lds_dwordx4 v[84:85], off
	v_lshl_add_u64 v[84:85], v[198:199], 0, s[8:9]
	s_mov_b32 m0, s65
	v_lshl_add_u64 v[200:201], s[66:67], 0, v[204:205]
	global_load_lds_dwordx4 v[84:85], off
	v_lshl_add_u64 v[84:85], v[198:199], 0, s[10:11]
	s_add_i32 m0, s65, 0x2000
	s_nop 0
	global_load_lds_dwordx4 v[84:85], off
	s_mov_b32 m0, s25
	v_lshl_add_u64 v[84:85], v[200:201], 0, s[12:13]
	global_load_lds_dwordx4 v[200:201], off
	s_mov_b32 m0, s26
	s_nop 0
	global_load_lds_dwordx4 v[84:85], off
	s_waitcnt vmcnt(8)
	s_waitcnt lgkmcnt(0)
	s_barrier
	s_waitcnt lgkmcnt(0)
	v_mfma_f32_16x16x32_bf16 v[62:65], v[68:71], v[166:169], 0
	v_mfma_f32_16x16x32_bf16 v[58:61], v[76:79], v[166:169], 0
	v_mfma_f32_16x16x32_bf16 v[46:49], v[68:71], v[174:177], 0
	v_mfma_f32_16x16x32_bf16 v[42:45], v[76:79], v[174:177], 0
	v_mfma_f32_16x16x32_bf16 v[30:33], v[68:71], v[182:185], 0
	v_mfma_f32_16x16x32_bf16 v[26:29], v[76:79], v[182:185], 0
	v_mfma_f32_16x16x32_bf16 v[14:17], v[68:71], v[190:193], 0
	v_mfma_f32_16x16x32_bf16 v[10:13], v[76:79], v[190:193], 0
	v_mfma_f32_16x16x32_bf16 v[62:65], v[72:75], v[170:173], v[62:65]
	v_mfma_f32_16x16x32_bf16 v[58:61], v[138:141], v[170:173], v[58:61]
	v_mfma_f32_16x16x32_bf16 v[46:49], v[72:75], v[178:181], v[46:49]
	v_mfma_f32_16x16x32_bf16 v[42:45], v[138:141], v[178:181], v[42:45]
	v_mfma_f32_16x16x32_bf16 v[30:33], v[72:75], v[186:189], v[30:33]
	v_mfma_f32_16x16x32_bf16 v[26:29], v[138:141], v[186:189], v[26:29]
	v_mfma_f32_16x16x32_bf16 v[14:17], v[72:75], v[194:197], v[14:17]
	v_mfma_f32_16x16x32_bf16 v[10:13], v[138:141], v[194:197], v[10:13]
	v_mfma_f32_16x16x32_bf16 v[54:57], v[142:145], v[166:169], 0
	v_mfma_f32_16x16x32_bf16 v[50:53], v[158:161], v[166:169], 0
	v_mfma_f32_16x16x32_bf16 v[38:41], v[142:145], v[174:177], 0
	v_mfma_f32_16x16x32_bf16 v[34:37], v[158:161], v[174:177], 0
	v_mfma_f32_16x16x32_bf16 v[22:25], v[142:145], v[182:185], 0
	v_mfma_f32_16x16x32_bf16 v[18:21], v[158:161], v[182:185], 0
	v_mfma_f32_16x16x32_bf16 v[6:9], v[142:145], v[190:193], 0
	v_mfma_f32_16x16x32_bf16 v[2:5], v[158:161], v[190:193], 0
	v_mfma_f32_16x16x32_bf16 v[54:57], v[154:157], v[170:173], v[54:57]
	v_mfma_f32_16x16x32_bf16 v[50:53], v[162:165], v[170:173], v[50:53]
	v_mfma_f32_16x16x32_bf16 v[38:41], v[154:157], v[178:181], v[38:41]
	v_mfma_f32_16x16x32_bf16 v[34:37], v[162:165], v[178:181], v[34:37]
	v_mfma_f32_16x16x32_bf16 v[22:25], v[154:157], v[186:189], v[22:25]
	v_mfma_f32_16x16x32_bf16 v[18:21], v[162:165], v[186:189], v[18:21]
	v_mfma_f32_16x16x32_bf16 v[6:9], v[154:157], v[194:197], v[6:9]
	v_mfma_f32_16x16x32_bf16 v[2:5], v[162:165], v[194:197], v[2:5]
	s_branch .Lmid_707

; #define G8_STA(bufoff, ptr, sg, h) G8_STAGE1(bufoff, (ptr) + (h) * ((sg) ? hA1 : hA0), ((sg) ? voffA1 : voffA0), ((sg) ? r64A1 : r64A0))
; #define G8_STB(bufoff, ptr, sg, h) G8_STAGE1(bufoff, (ptr) + (h) * ((sg) ? hB1 : hB0), ((sg) ? voffB1 : voffB0), ((sg) ? r64B1 : r64B0))
; #define G8_LDA(dst, b, h) do { _Pragma("unroll") for (int m = 0; m < 4; ++m) _Pragma("unroll") for (int k = 0; k < 2; ++k) dst[m][k] = *(const LAS bf16x8*)(lds + G8_SA(b, h) + aoff + m * 2048 + k * 1024); } while (0)
; #define G8_LDB(dst, b, h) do { _Pragma("unroll") for (int n = 0; n < 2; ++n) _Pragma("unroll") for (int k = 0; k < 2; ++k) dst[n][k] = *(const LAS bf16x8*)(lds + G8_SB(b, h) + boff + n * 2048 + k * 1024); } while (0)
; #define G8_MMA(ai, bj, At, Bt) do { __builtin_amdgcn_s_setprio(1); _Pragma("unroll") for (int m = 0; m < 4; ++m) _Pragma("unroll") for (int n = 0; n < 2; ++n) _Pragma("unroll") for (int k = 0; k < 2; ++k) \
;         acc[ai][bj][m][n] = __builtin_amdgcn_mfma_f32_16x16x32_bf16(Bt[n][k], At[m][k], acc[ai][bj][m][n], 0, 0, 0); __builtin_amdgcn_s_setprio(0); } while (0)
; #define G8_WAIT_V(n) asm volatile("s_waitcnt vmcnt(" #n ")" ::: "memory")
; #define G8_WAIT_L(n) asm volatile("s_waitcnt lgkmcnt(" #n ")" ::: "memory")
; #define G8_BAR __builtin_amdgcn_s_barrier()
; #define G8_SCHED __builtin_amdgcn_sched_barrier(0)
; template <class P>
; __device__ __forceinline__ void gemm_phase(LAS unsigned char* lds, const P& p, const int G, const int c) {
;     ...
;             G8_LDB(B0, 1, 0); G8_LDB(B1, 1, 1); G8_SCHED; G8_LDA(At, 1, 0); G8_STA(G8_SA(0, 1), a2, sg2, 1);
;             G8_WAIT_V(8); G8_WAIT_L(0); G8_BAR; G8_MMA(0, 0, At, B0); G8_MMA(0, 1, At, B1); G8_BAR; G8_SCHED;
;             G8_LDA(At, 1, 1); G8_STB(G8_SB(1, 0), b3, sg2, 0); G8_STB(G8_SB(1, 1), b3, sg2, 1); G8_STA(G8_SA(1, 0), a3, sg2, 0);
;             G8_WAIT_V(8); G8_WAIT_L(0); G8_BAR; G8_MMA(1, 0, At, B0); G8_MMA(1, 1, At, B1); G8_BAR; G8_SCHED;
;         }
.Lmid_707:
	s_barrier
	s_add_i32 s65, 0, 0x18000
	v_add_u32_e32 v84, s65, v229
	s_add_i32 s66, 0, 0x1c000
	ds_read_b128 v[68:71], v84
	ds_read_b128 v[72:75], v84 offset:1024
	ds_read_b128 v[76:79], v84 offset:2048
	ds_read_b128 v[138:141], v84 offset:3072
	v_add_u32_e32 v84, s66, v229
	ds_read_b128 v[142:145], v84
	ds_read_b128 v[154:157], v84 offset:1024
	ds_read_b128 v[158:161], v84 offset:2048
	ds_read_b128 v[162:165], v84 offset:3072
	s_mov_b32 m0, s27
	v_lshl_add_u64 v[84:85], v[200:201], 0, s[14:15]
	ds_read_b128 v[166:169], v232 offset:32768
	ds_read_b128 v[170:173], v232 offset:33792
	ds_read_b128 v[174:177], v232 offset:34816
	ds_read_b128 v[178:181], v232 offset:35840
	ds_read_b128 v[182:185], v232 offset:36864
	ds_read_b128 v[186:189], v232 offset:37888
	ds_read_b128 v[190:193], v232 offset:38912
	ds_read_b128 v[194:197], v232 offset:39936
	global_load_lds_dwordx4 v[84:85], off
	v_lshl_add_u64 v[84:85], v[200:201], 0, s[16:17]
	s_mov_b32 m0, s31
	s_nop 0
	global_load_lds_dwordx4 v[84:85], off
	s_waitcnt vmcnt(8)
	s_waitcnt lgkmcnt(0)
	s_barrier
	s_waitcnt lgkmcnt(0)
	v_mfma_f32_16x16x32_bf16 v[150:153], v[68:71], v[166:169], v[150:153]
	v_mfma_f32_16x16x32_bf16 v[146:149], v[76:79], v[166:169], v[146:149]
	v_mfma_f32_16x16x32_bf16 v[126:129], v[68:71], v[174:177], v[126:129]
	v_mfma_f32_16x16x32_bf16 v[122:125], v[76:79], v[174:177], v[122:125]
	v_mfma_f32_16x16x32_bf16 v[110:113], v[68:71], v[182:185], v[110:113]
	v_mfma_f32_16x16x32_bf16 v[106:109], v[76:79], v[182:185], v[106:109]
	v_mfma_f32_16x16x32_bf16 v[94:97], v[68:71], v[190:193], v[94:97]
	v_mfma_f32_16x16x32_bf16 v[90:93], v[76:79], v[190:193], v[90:93]
	v_mfma_f32_16x16x32_bf16 v[150:153], v[72:75], v[170:173], v[150:153]
	v_mfma_f32_16x16x32_bf16 v[146:149], v[138:141], v[170:173], v[146:149]
	v_mfma_f32_16x16x32_bf16 v[126:129], v[72:75], v[178:181], v[126:129]
	v_mfma_f32_16x16x32_bf16 v[122:125], v[138:141], v[178:181], v[122:125]
	v_mfma_f32_16x16x32_bf16 v[110:113], v[72:75], v[186:189], v[110:113]
	v_mfma_f32_16x16x32_bf16 v[106:109], v[138:141], v[186:189], v[106:109]
	v_mfma_f32_16x16x32_bf16 v[94:97], v[72:75], v[194:197], v[94:97]
	v_mfma_f32_16x16x32_bf16 v[90:93], v[138:141], v[194:197], v[90:93]
	v_mfma_f32_16x16x32_bf16 v[134:137], v[142:145], v[166:169], v[134:137]
	v_mfma_f32_16x16x32_bf16 v[130:133], v[158:161], v[166:169], v[130:133]
	v_mfma_f32_16x16x32_bf16 v[118:121], v[142:145], v[174:177], v[118:121]
	v_mfma_f32_16x16x32_bf16 v[114:117], v[158:161], v[174:177], v[114:117]
	v_mfma_f32_16x16x32_bf16 v[102:105], v[142:145], v[182:185], v[102:105]
	v_mfma_f32_16x16x32_bf16 v[98:101], v[158:161], v[182:185], v[98:101]
	v_mfma_f32_16x16x32_bf16 v[84:87], v[142:145], v[190:193], v[86:89]
	v_mfma_f32_16x16x32_bf16 v[80:83], v[158:161], v[190:193], v[80:83]
	v_mfma_f32_16x16x32_bf16 v[134:137], v[154:157], v[170:173], v[134:137]
	v_mfma_f32_16x16x32_bf16 v[130:133], v[162:165], v[170:173], v[130:133]
	v_mfma_f32_16x16x32_bf16 v[118:121], v[154:157], v[178:181], v[118:121]
	v_mfma_f32_16x16x32_bf16 v[114:117], v[162:165], v[178:181], v[114:117]
	v_mfma_f32_16x16x32_bf16 v[102:105], v[154:157], v[186:189], v[102:105]
	v_mfma_f32_16x16x32_bf16 v[98:101], v[162:165], v[186:189], v[98:101]
	v_mfma_f32_16x16x32_bf16 v[86:89], v[154:157], v[194:197], v[84:87]
	v_mfma_f32_16x16x32_bf16 v[82:85], v[162:165], v[194:197], v[80:83]
	s_barrier
	s_add_i32 s65, s65, s24
	v_lshl_add_u64 v[80:81], v[198:199], 0, s[36:37]
	s_mov_b32 m0, s65
	ds_read_b128 v[166:169], v232 offset:49152
	ds_read_b128 v[170:173], v232 offset:50176
	ds_read_b128 v[174:177], v232 offset:51200
	ds_read_b128 v[178:181], v232 offset:52224
	ds_read_b128 v[182:185], v232 offset:53248
	ds_read_b128 v[186:189], v232 offset:54272
	ds_read_b128 v[190:193], v232 offset:55296
	ds_read_b128 v[194:197], v232 offset:56320
	global_load_lds_dwordx4 v[80:81], off
	v_lshl_add_u64 v[80:81], v[198:199], 0, s[38:39]
	s_add_i32 m0, s65, 0x2000
	s_add_i32 s65, s66, s24
	global_load_lds_dwordx4 v[80:81], off
	v_lshl_add_u64 v[80:81], v[198:199], 0, s[44:45]
	s_mov_b32 m0, s65
	s_nop 0
	global_load_lds_dwordx4 v[80:81], off
	v_lshl_add_u64 v[80:81], v[198:199], 0, s[48:49]
	s_add_i32 m0, s65, 0x2000
	s_nop 0
	global_load_lds_dwordx4 v[80:81], off
	v_lshl_add_u64 v[80:81], v[200:201], 0, s[40:41]
	s_mov_b32 m0, s46
	s_nop 0
	global_load_lds_dwordx4 v[80:81], off
	v_lshl_add_u64 v[80:81], v[200:201], 0, s[42:43]
	s_mov_b32 m0, s47
	s_nop 0
	global_load_lds_dwordx4 v[80:81], off
	s_waitcnt vmcnt(8)
	s_waitcnt lgkmcnt(0)
	s_barrier
	s_waitcnt lgkmcnt(0)
	v_mfma_f32_16x16x32_bf16 v[62:65], v[68:71], v[166:169], v[62:65]
	v_mfma_f32_16x16x32_bf16 v[58:61], v[76:79], v[166:169], v[58:61]
	v_mfma_f32_16x16x32_bf16 v[46:49], v[68:71], v[174:177], v[46:49]
	v_mfma_f32_16x16x32_bf16 v[42:45], v[76:79], v[174:177], v[42:45]
	v_mfma_f32_16x16x32_bf16 v[30:33], v[68:71], v[182:185], v[30:33]
	v_mfma_f32_16x16x32_bf16 v[26:29], v[76:79], v[182:185], v[26:29]
	v_mfma_f32_16x16x32_bf16 v[14:17], v[68:71], v[190:193], v[14:17]
	v_mfma_f32_16x16x32_bf16 v[10:13], v[76:79], v[190:193], v[10:13]
	v_mfma_f32_16x16x32_bf16 v[62:65], v[72:75], v[170:173], v[62:65]
	v_mfma_f32_16x16x32_bf16 v[58:61], v[138:141], v[170:173], v[58:61]
	v_mfma_f32_16x16x32_bf16 v[46:49], v[72:75], v[178:181], v[46:49]
	v_mfma_f32_16x16x32_bf16 v[42:45], v[138:141], v[178:181], v[42:45]
	v_mfma_f32_16x16x32_bf16 v[30:33], v[72:75], v[186:189], v[30:33]
	v_mfma_f32_16x16x32_bf16 v[26:29], v[138:141], v[186:189], v[26:29]
	v_mfma_f32_16x16x32_bf16 v[14:17], v[72:75], v[194:197], v[14:17]
	v_mfma_f32_16x16x32_bf16 v[10:13], v[138:141], v[194:197], v[10:13]
	v_mfma_f32_16x16x32_bf16 v[54:57], v[142:145], v[166:169], v[54:57]
	v_mfma_f32_16x16x32_bf16 v[50:53], v[158:161], v[166:169], v[50:53]
	v_mfma_f32_16x16x32_bf16 v[38:41], v[142:145], v[174:177], v[38:41]
	v_mfma_f32_16x16x32_bf16 v[34:37], v[158:161], v[174:177], v[34:37]
	v_mfma_f32_16x16x32_bf16 v[22:25], v[142:145], v[182:185], v[22:25]
	v_mfma_f32_16x16x32_bf16 v[18:21], v[158:161], v[182:185], v[18:21]
	v_mfma_f32_16x16x32_bf16 v[6:9], v[142:145], v[190:193], v[6:9]
	v_mfma_f32_16x16x32_bf16 v[2:5], v[158:161], v[190:193], v[2:5]
	v_mfma_f32_16x16x32_bf16 v[54:57], v[154:157], v[170:173], v[54:57]
	v_mfma_f32_16x16x32_bf16 v[50:53], v[162:165], v[170:173], v[50:53]
	v_mfma_f32_16x16x32_bf16 v[38:41], v[154:157], v[178:181], v[38:41]
	v_mfma_f32_16x16x32_bf16 v[34:37], v[162:165], v[178:181], v[34:37]
	v_mfma_f32_16x16x32_bf16 v[22:25], v[154:157], v[186:189], v[22:25]
	v_mfma_f32_16x16x32_bf16 v[18:21], v[162:165], v[186:189], v[18:21]
	v_mfma_f32_16x16x32_bf16 v[6:9], v[154:157], v[194:197], v[6:9]
	v_mfma_f32_16x16x32_bf16 v[2:5], v[162:165], v[194:197], v[2:5]
	s_barrier
	s_add_i32 s64, s64, 2
	s_add_u32 s28, s28, 0x80000
	s_addc_u32 s29, s29, 0
	s_add_u32 s76, s76, 0x800000
	s_addc_u32 s77, s77, 0
	s_cmp_gt_u32 s64, 29
	s_cbranch_scc0 .LBB0_707
	s_and_b64 vcc, exec, s[52:53]
	s_cbranch_vccz .LBB0_710
	s_barrier

; #define G8_STA(bufoff, ptr, sg, h) G8_STAGE1(bufoff, (ptr) + (h) * ((sg) ? hA1 : hA0), ((sg) ? voffA1 : voffA0), ((sg) ? r64A1 : r64A0))
; #define G8_LDA(dst, b, h) do { _Pragma("unroll") for (int m = 0; m < 4; ++m) _Pragma("unroll") for (int k = 0; k < 2; ++k) dst[m][k] = *(const LAS bf16x8*)(lds + G8_SA(b, h) + aoff + m * 2048 + k * 1024); } while (0)
; #define G8_LDB(dst, b, h) do { _Pragma("unroll") for (int n = 0; n < 2; ++n) _Pragma("unroll") for (int k = 0; k < 2; ++k) dst[n][k] = *(const LAS bf16x8*)(lds + G8_SB(b, h) + boff + n * 2048 + k * 1024); } while (0)
; #define G8_MMA(ai, bj, At, Bt) do { __builtin_amdgcn_s_setprio(1); _Pragma("unroll") for (int m = 0; m < 4; ++m) _Pragma("unroll") for (int n = 0; n < 2; ++n) _Pragma("unroll") for (int k = 0; k < 2; ++k) \
;         acc[ai][bj][m][n] = __builtin_amdgcn_mfma_f32_16x16x32_bf16(Bt[n][k], At[m][k], acc[ai][bj][m][n], 0, 0, 0); __builtin_amdgcn_s_setprio(0); } while (0)
; #define G8_BAR __builtin_amdgcn_s_barrier()
; template <class P>
; __device__ __forceinline__ void gemm_phase(LAS unsigned char* lds, const P& p, const int G, const int c) {
;     ...
;         const bool has_next = p.unit((ui + 1) * G + c, nxt);
;         const int nt = p.nt(cur);
;         const char* nA0 = has_next ? p.a_base(nxt, 0) - p.a_bias(0) : cA0; const char* nA1 = has_next ? p.a_base(nxt, S1) - p.a_bias(S1) : cA1;
;         const char* nB0 = has_next ? p.b_base(nxt, 0) - p.b_bias(0) : cB0; const char* nB1 = has_next ? p.b_base(nxt, S1) - p.b_bias(S1) : cB1;
;         for (int t = 0; t < nt; t += 2) {
;             const bool last = (t == nt - 2);
;             const bool sg1 = (NS > 1) && (t + 1 >= nt0);
;             const bool sg2 = (NS > 1) && !last && (t + 2 >= nt0);
;             const char* a1 = sg1 ? cA1 + (long)(t + 1 - nt0) * ksA1 : cA0 + (long)(t + 1) * ksA0;
;             const char* a2 = last ? nA0 : (sg2 ? cA1 + (long)(t + 2 - nt0) * ksA1 : cA0 + (long)(t + 2) * ksA0);
;             const char* b2 = last ? nB0 : (sg2 ? cB1 + (long)(t + 2 - nt0) * ksB1 : cB0 + (long)(t + 2) * ksB0);
;             const char* a3 = a2 + (sg2 ? ksA1 : ksA0); const char* b3 = b2 + (sg2 ? ksB1 : ksB0);
;             G8_LDB(B0, 0, 0); G8_LDB(B1, 0, 1); G8_SCHED; G8_LDA(At, 0, 0); G8_STA(G8_SA(1, 1), a1, sg1, 1);
;             G8_WAIT_V(8); G8_WAIT_L(0); G8_BAR; G8_MMA(0, 0, At, B0); G8_MMA(0, 1, At, B1); G8_BAR; G8_SCHED;
.LBB0_769:
	s_ashr_i32 s57, s56, 31
	s_lshl_b64 s[18:19], s[56:57], 15
	s_add_u32 s60, s2, s18
	s_addc_u32 s61, s3, s19
	s_and_b64 s[18:19], s[54:55], exec
	s_cselect_b32 s18, s61, s71
	s_cselect_b32 s19, s60, s70
	s_ashr_i32 s59, s58, 31
	s_lshl_b64 s[62:63], s[58:59], 15
	s_add_u32 s62, s24, s62
	s_addc_u32 s63, s25, s63
	s_and_b64 s[72:73], s[54:55], exec
	s_cselect_b32 s57, s63, s29
	s_cselect_b32 s59, s62, s28
	s_add_u32 s28, s28, 0x40000
	s_addc_u32 s29, s29, 0
	v_lshl_add_u64 v[128:129], s[70:71], 0, v[152:153]
	s_mov_b32 s76, -2
	s_mov_b64 s[72:73], 0
	ds_read_b128 v[130:133], v158
	ds_read_b128 v[134:137], v158 offset:1024
	ds_read_b128 v[138:141], v158 offset:2048
	ds_read_b128 v[162:165], v158 offset:3072
	ds_read_b128 v[166:169], v159
	ds_read_b128 v[170:173], v159 offset:1024
	ds_read_b128 v[174:177], v159 offset:2048
	ds_read_b128 v[178:181], v159 offset:3072
	s_add_u32 s77, s70, s72
	s_addc_u32 s78, s71, s73
	s_add_u32 s77, s77, 0x800000
	s_addc_u32 s78, s78, 0
	s_cmp_eq_u32 s72, 0x7800000
	s_cselect_b32 s79, s18, s78
	s_cselect_b32 s78, s19, s77
	s_cselect_b32 s81, s57, s29
	s_cselect_b32 s80, s59, s28
	v_lshl_add_u64 v[142:143], v[128:129], 0, s[72:73]
	v_lshl_add_u64 v[154:155], v[142:143], 0, s[40:41]
	s_add_i32 m0, s27, 0xc000
	ds_read_b128 v[182:185], v160
	ds_read_b128 v[186:189], v160 offset:1024
	ds_read_b128 v[190:193], v160 offset:2048
	ds_read_b128 v[194:197], v160 offset:3072
	ds_read_b128 v[198:201], v160 offset:4096
	ds_read_b128 v[202:205], v160 offset:5120
	ds_read_b128 v[210:213], v160 offset:6144
	ds_read_b128 v[214:217], v160 offset:7168
	global_load_lds_dwordx4 v[154:155], off
	v_lshl_add_u64 v[142:143], v[142:143], 0, s[42:43]
	s_add_i32 m0, s27, 0xe000
	s_nop 0
	global_load_lds_dwordx4 v[142:143], off
	s_waitcnt vmcnt(8)
	s_waitcnt lgkmcnt(0)
	s_barrier
	s_waitcnt lgkmcnt(0)
	v_mfma_f32_16x16x32_bf16 v[120:123], v[130:133], v[182:185], 0
	v_mfma_f32_16x16x32_bf16 v[124:127], v[138:141], v[182:185], 0
	v_mfma_f32_16x16x32_bf16 v[112:115], v[130:133], v[190:193], 0
	v_mfma_f32_16x16x32_bf16 v[116:119], v[138:141], v[190:193], 0
	v_mfma_f32_16x16x32_bf16 v[100:103], v[130:133], v[198:201], 0
	v_mfma_f32_16x16x32_bf16 v[108:111], v[138:141], v[198:201], 0
	v_mfma_f32_16x16x32_bf16 v[84:87], v[130:133], v[210:213], 0
	v_mfma_f32_16x16x32_bf16 v[72:75], v[138:141], v[210:213], 0
	v_mfma_f32_16x16x32_bf16 v[120:123], v[134:137], v[186:189], v[120:123]
	v_mfma_f32_16x16x32_bf16 v[124:127], v[162:165], v[186:189], v[124:127]
	v_mfma_f32_16x16x32_bf16 v[112:115], v[134:137], v[194:197], v[112:115]
	v_mfma_f32_16x16x32_bf16 v[116:119], v[162:165], v[194:197], v[116:119]
	v_mfma_f32_16x16x32_bf16 v[100:103], v[134:137], v[202:205], v[100:103]
	v_mfma_f32_16x16x32_bf16 v[108:111], v[162:165], v[202:205], v[108:111]
	v_mfma_f32_16x16x32_bf16 v[84:87], v[134:137], v[214:217], v[84:87]
	v_mfma_f32_16x16x32_bf16 v[72:75], v[162:165], v[214:217], v[72:75]
	v_mfma_f32_16x16x32_bf16 v[104:107], v[166:169], v[182:185], 0
	v_mfma_f32_16x16x32_bf16 v[92:95], v[174:177], v[182:185], 0
	v_mfma_f32_16x16x32_bf16 v[96:99], v[166:169], v[190:193], 0
	v_mfma_f32_16x16x32_bf16 v[80:83], v[174:177], v[190:193], 0
	v_mfma_f32_16x16x32_bf16 v[88:91], v[166:169], v[198:201], 0
	v_mfma_f32_16x16x32_bf16 v[76:79], v[174:177], v[198:201], 0
	v_mfma_f32_16x16x32_bf16 v[68:71], v[166:169], v[210:213], 0
	v_mfma_f32_16x16x32_bf16 v[64:67], v[174:177], v[210:213], 0
	v_mfma_f32_16x16x32_bf16 v[104:107], v[170:173], v[186:189], v[104:107]
	v_mfma_f32_16x16x32_bf16 v[92:95], v[178:181], v[186:189], v[92:95]
	v_mfma_f32_16x16x32_bf16 v[96:99], v[170:173], v[194:197], v[96:99]
	v_mfma_f32_16x16x32_bf16 v[80:83], v[178:181], v[194:197], v[80:83]
	v_mfma_f32_16x16x32_bf16 v[88:91], v[170:173], v[202:205], v[88:91]
	v_mfma_f32_16x16x32_bf16 v[76:79], v[178:181], v[202:205], v[76:79]
	v_mfma_f32_16x16x32_bf16 v[68:71], v[170:173], v[214:217], v[68:71]
	v_mfma_f32_16x16x32_bf16 v[64:67], v[178:181], v[214:217], v[64:67]
	s_barrier
; #define G8_STA(bufoff, ptr, sg, h) G8_STAGE1(bufoff, (ptr) + (h) * ((sg) ? hA1 : hA0), ((sg) ? voffA1 : voffA0), ((sg) ? r64A1 : r64A0))
; #define G8_STB(bufoff, ptr, sg, h) G8_STAGE1(bufoff, (ptr) + (h) * ((sg) ? hB1 : hB0), ((sg) ? voffB1 : voffB0), ((sg) ? r64B1 : r64B0))
; #define G8_LDA(dst, b, h) do { _Pragma("unroll") for (int m = 0; m < 4; ++m) _Pragma("unroll") for (int k = 0; k < 2; ++k) dst[m][k] = *(const LAS bf16x8*)(lds + G8_SA(b, h) + aoff + m * 2048 + k * 1024); } while (0)
; #define G8_MMA(ai, bj, At, Bt) do { __builtin_amdgcn_s_setprio(1); _Pragma("unroll") for (int m = 0; m < 4; ++m) _Pragma("unroll") for (int n = 0; n < 2; ++n) _Pragma("unroll") for (int k = 0; k < 2; ++k) \
;         acc[ai][bj][m][n] = __builtin_amdgcn_mfma_f32_16x16x32_bf16(Bt[n][k], At[m][k], acc[ai][bj][m][n], 0, 0, 0); __builtin_amdgcn_s_setprio(0); } while (0)
; #define G8_WAIT_V(n) asm volatile("s_waitcnt vmcnt(" #n ")" ::: "memory")
; #define G8_WAIT_L(n) asm volatile("s_waitcnt lgkmcnt(" #n ")" ::: "memory")
; #define G8_BAR __builtin_amdgcn_s_barrier()
; #define G8_SCHED __builtin_amdgcn_sched_barrier(0)
; template <class P>
; __device__ __forceinline__ void gemm_phase(LAS unsigned char* lds, const P& p, const int G, const int c) {
;     ...
;             G8_LDA(At, 0, 1); G8_STB(G8_SB(0, 0), b2, sg2, 0); G8_STB(G8_SB(0, 1), b2, sg2, 1); G8_STA(G8_SA(0, 0), a2, sg2, 0);
;             G8_WAIT_V(8); G8_WAIT_L(0); G8_BAR; G8_MMA(1, 0, At, B0); G8_MMA(1, 1, At, B1); G8_BAR; G8_SCHED;
	s_add_i32 s77, s30, s26
	v_lshl_add_u64 v[142:143], s[80:81], 0, v[144:145]
	s_mov_b32 m0, s77
	ds_read_b128 v[182:185], v160 offset:16384
	ds_read_b128 v[186:189], v160 offset:17408
	ds_read_b128 v[190:193], v160 offset:18432
	ds_read_b128 v[194:197], v160 offset:19456
	ds_read_b128 v[198:201], v160 offset:20480
	ds_read_b128 v[202:205], v160 offset:21504
	ds_read_b128 v[210:213], v160 offset:22528
	ds_read_b128 v[214:217], v160 offset:23552
	global_load_lds_dwordx4 v[142:143], off
	v_lshl_add_u64 v[154:155], v[142:143], 0, s[4:5]
	s_add_i32 m0, s77, 0x2000
	s_add_i32 s77, s74, s26
	global_load_lds_dwordx4 v[154:155], off
	v_lshl_add_u64 v[154:155], v[142:143], 0, s[6:7]
	s_mov_b32 m0, s77
	s_nop 0
	global_load_lds_dwordx4 v[154:155], off
	v_lshl_add_u64 v[154:155], v[142:143], 0, s[8:9]
	s_add_i32 m0, s77, 0x2000
	s_nop 0
	global_load_lds_dwordx4 v[154:155], off
	v_lshl_add_u64 v[154:155], s[78:79], 0, v[146:147]
	s_mov_b32 m0, s27
	v_lshl_add_u64 v[206:207], v[154:155], 0, s[4:5]
	global_load_lds_dwordx4 v[154:155], off
	s_mov_b32 m0, s31
	s_nop 0
	global_load_lds_dwordx4 v[206:207], off
	s_waitcnt vmcnt(8)
	s_waitcnt lgkmcnt(0)
	s_barrier
	s_waitcnt lgkmcnt(0)
	v_mfma_f32_16x16x32_bf16 v[60:63], v[130:133], v[182:185], 0
	v_mfma_f32_16x16x32_bf16 v[56:59], v[138:141], v[182:185], 0
	v_mfma_f32_16x16x32_bf16 v[52:55], v[130:133], v[190:193], 0
	v_mfma_f32_16x16x32_bf16 v[44:47], v[138:141], v[190:193], 0
	v_mfma_f32_16x16x32_bf16 v[36:39], v[130:133], v[198:201], 0
	v_mfma_f32_16x16x32_bf16 v[28:31], v[138:141], v[198:201], 0
	v_mfma_f32_16x16x32_bf16 v[20:23], v[130:133], v[210:213], 0
	v_mfma_f32_16x16x32_bf16 v[12:15], v[138:141], v[210:213], 0
	v_mfma_f32_16x16x32_bf16 v[60:63], v[134:137], v[186:189], v[60:63]
	v_mfma_f32_16x16x32_bf16 v[56:59], v[162:165], v[186:189], v[56:59]
	v_mfma_f32_16x16x32_bf16 v[52:55], v[134:137], v[194:197], v[52:55]
	v_mfma_f32_16x16x32_bf16 v[44:47], v[162:165], v[194:197], v[44:47]
	v_mfma_f32_16x16x32_bf16 v[36:39], v[134:137], v[202:205], v[36:39]
	v_mfma_f32_16x16x32_bf16 v[28:31], v[162:165], v[202:205], v[28:31]
	v_mfma_f32_16x16x32_bf16 v[20:23], v[134:137], v[214:217], v[20:23]
	v_mfma_f32_16x16x32_bf16 v[12:15], v[162:165], v[214:217], v[12:15]
	v_mfma_f32_16x16x32_bf16 v[48:51], v[166:169], v[182:185], 0
	v_mfma_f32_16x16x32_bf16 v[40:43], v[174:177], v[182:185], 0
	v_mfma_f32_16x16x32_bf16 v[32:35], v[166:169], v[190:193], 0
	v_mfma_f32_16x16x32_bf16 v[24:27], v[174:177], v[190:193], 0
	v_mfma_f32_16x16x32_bf16 v[16:19], v[166:169], v[198:201], 0
	v_mfma_f32_16x16x32_bf16 v[8:11], v[174:177], v[198:201], 0
	v_mfma_f32_16x16x32_bf16 v[4:7], v[166:169], v[210:213], 0
	v_mfma_f32_16x16x32_bf16 v[0:3], v[174:177], v[210:213], 0
	v_mfma_f32_16x16x32_bf16 v[48:51], v[170:173], v[186:189], v[48:51]
	v_mfma_f32_16x16x32_bf16 v[40:43], v[178:181], v[186:189], v[40:43]
	v_mfma_f32_16x16x32_bf16 v[32:35], v[170:173], v[194:197], v[32:35]
	v_mfma_f32_16x16x32_bf16 v[24:27], v[178:181], v[194:197], v[24:27]
	v_mfma_f32_16x16x32_bf16 v[16:19], v[170:173], v[202:205], v[16:19]
	v_mfma_f32_16x16x32_bf16 v[8:11], v[178:181], v[202:205], v[8:11]
	v_mfma_f32_16x16x32_bf16 v[4:7], v[170:173], v[214:217], v[4:7]
	v_mfma_f32_16x16x32_bf16 v[0:3], v[178:181], v[214:217], v[0:3]
	s_branch .Lmid_770

; #define G8_STA(bufoff, ptr, sg, h) G8_STAGE1(bufoff, (ptr) + (h) * ((sg) ? hA1 : hA0), ((sg) ? voffA1 : voffA0), ((sg) ? r64A1 : r64A0))
; #define G8_STB(bufoff, ptr, sg, h) G8_STAGE1(bufoff, (ptr) + (h) * ((sg) ? hB1 : hB0), ((sg) ? voffB1 : voffB0), ((sg) ? r64B1 : r64B0))
; #define G8_LDA(dst, b, h) do { _Pragma("unroll") for (int m = 0; m < 4; ++m) _Pragma("unroll") for (int k = 0; k < 2; ++k) dst[m][k] = *(const LAS bf16x8*)(lds + G8_SA(b, h) + aoff + m * 2048 + k * 1024); } while (0)
; #define G8_LDB(dst, b, h) do { _Pragma("unroll") for (int n = 0; n < 2; ++n) _Pragma("unroll") for (int k = 0; k < 2; ++k) dst[n][k] = *(const LAS bf16x8*)(lds + G8_SB(b, h) + boff + n * 2048 + k * 1024); } while (0)
; #define G8_MMA(ai, bj, At, Bt) do { __builtin_amdgcn_s_setprio(1); _Pragma("unroll") for (int m = 0; m < 4; ++m) _Pragma("unroll") for (int n = 0; n < 2; ++n) _Pragma("unroll") for (int k = 0; k < 2; ++k) \
;         acc[ai][bj][m][n] = __builtin_amdgcn_mfma_f32_16x16x32_bf16(Bt[n][k], At[m][k], acc[ai][bj][m][n], 0, 0, 0); __builtin_amdgcn_s_setprio(0); } while (0)
; #define G8_WAIT_V(n) asm volatile("s_waitcnt vmcnt(" #n ")" ::: "memory")
; #define G8_WAIT_L(n) asm volatile("s_waitcnt lgkmcnt(" #n ")" ::: "memory")
; #define G8_BAR __builtin_amdgcn_s_barrier()
; #define G8_SCHED __builtin_amdgcn_sched_barrier(0)
; template <class P>
; __device__ __forceinline__ void gemm_phase(LAS unsigned char* lds, const P& p, const int G, const int c) {
;     ...
;             G8_LDB(B0, 1, 0); G8_LDB(B1, 1, 1); G8_SCHED; G8_LDA(At, 1, 0); G8_STA(G8_SA(0, 1), a2, sg2, 1);
;             G8_WAIT_V(8); G8_WAIT_L(0); G8_BAR; G8_MMA(0, 0, At, B0); G8_MMA(0, 1, At, B1); G8_BAR; G8_SCHED;
;             G8_LDA(At, 1, 1); G8_STB(G8_SB(1, 0), b3, sg2, 0); G8_STB(G8_SB(1, 1), b3, sg2, 1); G8_STA(G8_SA(1, 0), a3, sg2, 0);
;             G8_WAIT_V(8); G8_WAIT_L(0); G8_BAR; G8_MMA(1, 0, At, B0); G8_MMA(1, 1, At, B1); G8_BAR; G8_SCHED;
;         }
.Lmid_770:
	s_barrier
	s_add_i32 s77, 0, 0x18000
	v_add_u32_e32 v161, s77, v156
	s_add_i32 s78, 0, 0x1c000
	ds_read_b128 v[130:133], v161
	ds_read_b128 v[134:137], v161 offset:1024
	ds_read_b128 v[138:141], v161 offset:2048
	ds_read_b128 v[162:165], v161 offset:3072
	v_add_u32_e32 v161, s78, v156
	ds_read_b128 v[166:169], v161
	ds_read_b128 v[170:173], v161 offset:1024
	ds_read_b128 v[174:177], v161 offset:2048
	ds_read_b128 v[178:181], v161 offset:3072
	s_mov_b32 m0, s33
	v_lshl_add_u64 v[206:207], v[154:155], 0, s[6:7]
	ds_read_b128 v[182:185], v160 offset:32768
	ds_read_b128 v[186:189], v160 offset:33792
	ds_read_b128 v[190:193], v160 offset:34816
	ds_read_b128 v[194:197], v160 offset:35840
	ds_read_b128 v[198:201], v160 offset:36864
	ds_read_b128 v[202:205], v160 offset:37888
	ds_read_b128 v[210:213], v160 offset:38912
	ds_read_b128 v[214:217], v160 offset:39936
	global_load_lds_dwordx4 v[206:207], off
	v_lshl_add_u64 v[206:207], v[154:155], 0, s[8:9]
	s_mov_b32 m0, s34
	s_nop 0
	global_load_lds_dwordx4 v[206:207], off
	s_waitcnt vmcnt(8)
	s_waitcnt lgkmcnt(0)
	s_barrier
	s_waitcnt lgkmcnt(0)
	v_mfma_f32_16x16x32_bf16 v[120:123], v[130:133], v[182:185], v[120:123]
	v_mfma_f32_16x16x32_bf16 v[124:127], v[138:141], v[182:185], v[124:127]
	v_mfma_f32_16x16x32_bf16 v[112:115], v[130:133], v[190:193], v[112:115]
	v_mfma_f32_16x16x32_bf16 v[116:119], v[138:141], v[190:193], v[116:119]
	v_mfma_f32_16x16x32_bf16 v[100:103], v[130:133], v[198:201], v[100:103]
	v_mfma_f32_16x16x32_bf16 v[108:111], v[138:141], v[198:201], v[108:111]
	v_mfma_f32_16x16x32_bf16 v[84:87], v[130:133], v[210:213], v[84:87]
	v_mfma_f32_16x16x32_bf16 v[72:75], v[138:141], v[210:213], v[72:75]
	v_mfma_f32_16x16x32_bf16 v[120:123], v[134:137], v[186:189], v[120:123]
	v_mfma_f32_16x16x32_bf16 v[124:127], v[162:165], v[186:189], v[124:127]
	v_mfma_f32_16x16x32_bf16 v[112:115], v[134:137], v[194:197], v[112:115]
	v_mfma_f32_16x16x32_bf16 v[116:119], v[162:165], v[194:197], v[116:119]
	v_mfma_f32_16x16x32_bf16 v[100:103], v[134:137], v[202:205], v[100:103]
	v_mfma_f32_16x16x32_bf16 v[108:111], v[162:165], v[202:205], v[108:111]
	v_mfma_f32_16x16x32_bf16 v[84:87], v[134:137], v[214:217], v[84:87]
	v_mfma_f32_16x16x32_bf16 v[72:75], v[162:165], v[214:217], v[72:75]
	v_mfma_f32_16x16x32_bf16 v[104:107], v[166:169], v[182:185], v[104:107]
	v_mfma_f32_16x16x32_bf16 v[92:95], v[174:177], v[182:185], v[92:95]
	v_mfma_f32_16x16x32_bf16 v[96:99], v[166:169], v[190:193], v[96:99]
	v_mfma_f32_16x16x32_bf16 v[80:83], v[174:177], v[190:193], v[80:83]
	v_mfma_f32_16x16x32_bf16 v[88:91], v[166:169], v[198:201], v[88:91]
	v_mfma_f32_16x16x32_bf16 v[76:79], v[174:177], v[198:201], v[76:79]
	v_mfma_f32_16x16x32_bf16 v[68:71], v[166:169], v[210:213], v[68:71]
	v_mfma_f32_16x16x32_bf16 v[64:67], v[174:177], v[210:213], v[64:67]
	v_mfma_f32_16x16x32_bf16 v[104:107], v[170:173], v[186:189], v[104:107]
	v_mfma_f32_16x16x32_bf16 v[92:95], v[178:181], v[186:189], v[92:95]
	v_mfma_f32_16x16x32_bf16 v[96:99], v[170:173], v[194:197], v[96:99]
	v_mfma_f32_16x16x32_bf16 v[80:83], v[178:181], v[194:197], v[80:83]
	v_mfma_f32_16x16x32_bf16 v[88:91], v[170:173], v[202:205], v[88:91]
	v_mfma_f32_16x16x32_bf16 v[76:79], v[178:181], v[202:205], v[76:79]
	v_mfma_f32_16x16x32_bf16 v[68:71], v[170:173], v[214:217], v[68:71]
	v_mfma_f32_16x16x32_bf16 v[64:67], v[178:181], v[214:217], v[64:67]
	s_barrier
	s_add_i32 s77, s77, s26
	v_lshl_add_u64 v[206:207], v[142:143], 0, s[12:13]
	s_mov_b32 m0, s77
	ds_read_b128 v[182:185], v160 offset:49152
	ds_read_b128 v[186:189], v160 offset:50176
	ds_read_b128 v[190:193], v160 offset:51200
	ds_read_b128 v[194:197], v160 offset:52224
	ds_read_b128 v[198:201], v160 offset:53248
	ds_read_b128 v[202:205], v160 offset:54272
	ds_read_b128 v[210:213], v160 offset:55296
	ds_read_b128 v[214:217], v160 offset:56320
	global_load_lds_dwordx4 v[206:207], off
	v_lshl_add_u64 v[206:207], v[142:143], 0, s[14:15]
	s_add_i32 m0, s77, 0x2000
	s_add_i32 s77, s78, s26
	global_load_lds_dwordx4 v[206:207], off
	v_lshl_add_u64 v[206:207], v[142:143], 0, s[22:23]
	s_mov_b32 m0, s77
	v_lshl_add_u64 v[142:143], v[142:143], 0, s[36:37]
	global_load_lds_dwordx4 v[206:207], off
	s_add_i32 m0, s77, 0x2000
	s_nop 0
	global_load_lds_dwordx4 v[142:143], off
	v_lshl_add_u64 v[142:143], v[154:155], 0, s[16:17]
	s_mov_b32 m0, s67
	s_nop 0
	global_load_lds_dwordx4 v[142:143], off
	v_lshl_add_u64 v[142:143], v[154:155], 0, s[20:21]
	s_mov_b32 m0, s69
	s_nop 0
	global_load_lds_dwordx4 v[142:143], off
	s_waitcnt vmcnt(8)
	s_waitcnt lgkmcnt(0)
	s_barrier
	s_waitcnt lgkmcnt(0)
	v_mfma_f32_16x16x32_bf16 v[60:63], v[130:133], v[182:185], v[60:63]
	v_mfma_f32_16x16x32_bf16 v[56:59], v[138:141], v[182:185], v[56:59]
	v_mfma_f32_16x16x32_bf16 v[52:55], v[130:133], v[190:193], v[52:55]
	v_mfma_f32_16x16x32_bf16 v[44:47], v[138:141], v[190:193], v[44:47]
	v_mfma_f32_16x16x32_bf16 v[36:39], v[130:133], v[198:201], v[36:39]
	v_mfma_f32_16x16x32_bf16 v[28:31], v[138:141], v[198:201], v[28:31]
	v_mfma_f32_16x16x32_bf16 v[20:23], v[130:133], v[210:213], v[20:23]
	v_mfma_f32_16x16x32_bf16 v[12:15], v[138:141], v[210:213], v[12:15]
	v_mfma_f32_16x16x32_bf16 v[60:63], v[134:137], v[186:189], v[60:63]
	v_mfma_f32_16x16x32_bf16 v[56:59], v[162:165], v[186:189], v[56:59]
	v_mfma_f32_16x16x32_bf16 v[52:55], v[134:137], v[194:197], v[52:55]
	v_mfma_f32_16x16x32_bf16 v[44:47], v[162:165], v[194:197], v[44:47]
	v_mfma_f32_16x16x32_bf16 v[36:39], v[134:137], v[202:205], v[36:39]
	v_mfma_f32_16x16x32_bf16 v[28:31], v[162:165], v[202:205], v[28:31]
	v_mfma_f32_16x16x32_bf16 v[20:23], v[134:137], v[214:217], v[20:23]
	v_mfma_f32_16x16x32_bf16 v[12:15], v[162:165], v[214:217], v[12:15]
	v_mfma_f32_16x16x32_bf16 v[48:51], v[166:169], v[182:185], v[48:51]
	v_mfma_f32_16x16x32_bf16 v[40:43], v[174:177], v[182:185], v[40:43]
	v_mfma_f32_16x16x32_bf16 v[32:35], v[166:169], v[190:193], v[32:35]
	v_mfma_f32_16x16x32_bf16 v[24:27], v[174:177], v[190:193], v[24:27]
	v_mfma_f32_16x16x32_bf16 v[16:19], v[166:169], v[198:201], v[16:19]
	v_mfma_f32_16x16x32_bf16 v[8:11], v[174:177], v[198:201], v[8:11]
	v_mfma_f32_16x16x32_bf16 v[4:7], v[166:169], v[210:213], v[4:7]
	v_mfma_f32_16x16x32_bf16 v[0:3], v[174:177], v[210:213], v[0:3]
	v_mfma_f32_16x16x32_bf16 v[48:51], v[170:173], v[186:189], v[48:51]
	v_mfma_f32_16x16x32_bf16 v[40:43], v[178:181], v[186:189], v[40:43]
	v_mfma_f32_16x16x32_bf16 v[32:35], v[170:173], v[194:197], v[32:35]
	v_mfma_f32_16x16x32_bf16 v[24:27], v[178:181], v[194:197], v[24:27]
	v_mfma_f32_16x16x32_bf16 v[16:19], v[170:173], v[202:205], v[16:19]
	v_mfma_f32_16x16x32_bf16 v[8:11], v[178:181], v[202:205], v[8:11]
	v_mfma_f32_16x16x32_bf16 v[4:7], v[170:173], v[214:217], v[4:7]
	v_mfma_f32_16x16x32_bf16 v[0:3], v[178:181], v[214:217], v[0:3]
	s_barrier
	s_add_i32 s76, s76, 2
	s_add_u32 s28, s28, 0x40000
	s_addc_u32 s29, s29, 0
	s_add_u32 s72, s72, 0x800000
	s_addc_u32 s73, s73, 0
	s_cmp_gt_u32 s76, 29
	s_cbranch_scc0 .LBB0_770
	s_and_b64 vcc, exec, s[38:39]
	s_cbranch_vccz .LBB0_773
	s_barrier
